# speedup vs baseline: 1.1129x; 1.0096x over previous
.LBB0_169:
	v_max_u32_dpp v103, v99, v99 quad_perm:[1,0,3,2] row_mask:0xf bank_mask:0xf
	s_nop 1
	v_max_u32_dpp v103, v103, v103 quad_perm:[2,3,0,1] row_mask:0xf bank_mask:0xf
	s_nop 1
	v_max_u32_dpp v103, v103, v103 row_half_mirror row_mask:0xf bank_mask:0xf
	s_nop 1
	v_max_u32_dpp v103, v103, v103 row_mirror row_mask:0xf bank_mask:0xf
	v_cmp_eq_u32_e32 vcc, v99, v103
	s_nop 1
	v_cndmask_b32_e32 v99, v99, v101, vcc
	v_cndmask_b32_e32 v101, v101, v102, vcc
	v_cndmask_b32_e32 v102, v102, v100, vcc
	v_cndmask_b32_e64 v100, v100, 0, vcc
	v_cmp_eq_u32_e32 vcc, s0, v83
	s_add_i32 s0, s0, 1
	s_cmp_lg_u32 s0, 16
	v_cndmask_b32_e32 v98, v98, v103, vcc
	s_cbranch_scc1 .LBB0_169
	v_not_b32_e32 v99, v98
	v_lshrrev_b32_e32 v99, 4, v99
	v_and_or_b32 v99, v99, 15, v156
	v_lshlrev_b32_e32 v99, 2, v99
	v_cmp_lt_i32_e32 vcc, -1, v98
	ds_bpermute_b32 v96, v99, v96
	s_movk_i32 s0, 0xff00
	v_cndmask_b32_e64 v99, v189, -1, vcc
	v_bitop3_b32 v99, v99, v98, s0 bitop3:0x78
	ds_bpermute_b32 v100, v157, v99
	v_bitop3_b32 v98, v98, v156, 15 bitop3:0xce
	v_lshlrev_b32_e32 v98, 2, v98
	ds_bpermute_b32 v97, v98, v97
	s_waitcnt lgkmcnt(2)
	v_lshlrev_b32_e32 v96, 7, v96
	s_waitcnt lgkmcnt(1)
	v_sub_f32_e32 v98, v99, v100
	v_mul_f32_e32 v98, 0x3fb8aa3b, v98
	v_exp_f32_e32 v112, v98
	v_and_b32_e32 v96, 0x3f80, v96
	s_waitcnt lgkmcnt(0)
	v_and_b32_e32 v97, 0x7f, v97
	v_bitop3_b32 v113, v97, s74, v96 bitop3:0x36
	v_add_f32_dpp v96, v112, v112 quad_perm:[1,0,3,2] row_mask:0xf bank_mask:0xf bound_ctrl:1
	v_readlane_b32 s0, v254, 52
	s_waitcnt vmcnt(18)
	v_lshlrev_b32_e32 v120, 16, v46
	v_add_f32_dpp v96, v96, v96 quad_perm:[2,3,0,1] row_mask:0xf bank_mask:0xf bound_ctrl:1
	v_add_u32_e32 v226, s0, v94
	v_and_b32_e32 v121, 0xffff0000, v46
	v_add_f32_dpp v96, v96, v96 row_half_mirror row_mask:0xf bank_mask:0xf bound_ctrl:1
	v_lshlrev_b32_e32 v46, 16, v47
	v_and_b32_e32 v47, 0xffff0000, v47
	v_add_f32_dpp v114, v96, v96 row_mirror row_mask:0xf bank_mask:0xf bound_ctrl:1
	v_min_i32_e32 v96, 0x3fff, v226
	v_ashrrev_i32_e32 v97, 31, v96
	v_lshlrev_b64 v[96:97], 12, v[96:97]
	v_lshl_add_u64 v[96:97], v[92:93], 0, v[96:97]
	global_load_dwordx2 v[110:111], v[96:97], off
	global_load_dwordx2 v[108:109], v[96:97], off offset:512
	global_load_dwordx2 v[106:107], v[96:97], off offset:1024
	global_load_dwordx2 v[104:105], v[96:97], off offset:1536
	global_load_dwordx2 v[102:103], v[96:97], off offset:2048
	global_load_dwordx2 v[100:101], v[96:97], off offset:2560
	global_load_dwordx2 v[98:99], v[96:97], off offset:3072
	s_nop 0
	global_load_dwordx2 v[96:97], v[96:97], off offset:3584
	v_div_scale_f32 v115, s[6:7], v114, v114, v112
	v_rcp_f32_e32 v116, v115
	v_lshlrev_b32_e32 v122, 16, v48
	v_and_b32_e32 v123, 0xffff0000, v48
	v_lshlrev_b32_e32 v48, 16, v49
	v_fma_f32 v117, -v115, v116, 1.0
	v_fmac_f32_e32 v116, v117, v116
	v_div_scale_f32 v117, vcc, v112, v114, v112
	v_mul_f32_e32 v118, v117, v116
	v_fma_f32 v119, -v115, v118, v117
	v_fmac_f32_e32 v118, v119, v116
	v_fma_f32 v115, -v115, v118, v117
	v_div_fmas_f32 v115, v115, v116, v118
	v_div_fixup_f32 v112, v115, v114, v112
	ds_write2st64_b32 v154, v112, v113 offset0:137 offset1:139
	s_waitcnt vmcnt(24)
	v_lshlrev_b32_e32 v112, 16, v54
	v_and_b32_e32 v113, 0xffff0000, v54
	v_lshlrev_b32_e32 v54, 16, v55
	v_and_b32_e32 v55, 0xffff0000, v55
	v_lshlrev_b32_e32 v114, 16, v56
	v_and_b32_e32 v115, 0xffff0000, v56
	v_lshlrev_b32_e32 v56, 16, v57
	v_and_b32_e32 v57, 0xffff0000, v57
	v_lshlrev_b32_e32 v116, 16, v50
	v_and_b32_e32 v117, 0xffff0000, v50
	v_lshlrev_b32_e32 v50, 16, v51
	v_and_b32_e32 v51, 0xffff0000, v51
	v_lshlrev_b32_e32 v118, 16, v52
	v_and_b32_e32 v119, 0xffff0000, v52
	v_lshlrev_b32_e32 v52, 16, v53
	v_and_b32_e32 v53, 0xffff0000, v53
	v_and_b32_e32 v49, 0xffff0000, v49
	v_lshlrev_b32_e32 v126, 16, v38
	v_and_b32_e32 v127, 0xffff0000, v38
	v_lshlrev_b32_e32 v38, 16, v39
	v_and_b32_e32 v39, 0xffff0000, v39
	v_lshlrev_b32_e32 v128, 16, v40
	v_and_b32_e32 v129, 0xffff0000, v40
	v_lshlrev_b32_e32 v40, 16, v41
	v_and_b32_e32 v41, 0xffff0000, v41
	s_waitcnt vmcnt(20)
	v_lshlrev_b32_e32 v130, 16, v42
	v_and_b32_e32 v131, 0xffff0000, v42
	v_lshlrev_b32_e32 v42, 16, v43
	v_and_b32_e32 v43, 0xffff0000, v43
	v_lshlrev_b32_e32 v132, 16, v44
	v_and_b32_e32 v133, 0xffff0000, v44
	v_lshlrev_b32_e32 v44, 16, v45
	v_and_b32_e32 v45, 0xffff0000, v45
	v_lshlrev_b32_e32 v134, 16, v34
	v_and_b32_e32 v135, 0xffff0000, v34
	v_lshlrev_b32_e32 v34, 16, v35
	v_and_b32_e32 v35, 0xffff0000, v35
	v_lshlrev_b32_e32 v136, 16, v36
	v_and_b32_e32 v137, 0xffff0000, v36
	v_lshlrev_b32_e32 v36, 16, v37
	v_and_b32_e32 v37, 0xffff0000, v37
	v_lshlrev_b32_e32 v138, 16, v30
	v_and_b32_e32 v139, 0xffff0000, v30
	v_lshlrev_b32_e32 v140, 16, v31
	v_and_b32_e32 v141, 0xffff0000, v31
	v_lshlrev_b32_e32 v142, 16, v32
	v_and_b32_e32 v143, 0xffff0000, v32
	v_lshlrev_b32_e32 v144, 16, v33
	v_and_b32_e32 v145, 0xffff0000, v33
	v_lshlrev_b32_e32 v146, 16, v26
	v_and_b32_e32 v147, 0xffff0000, v26
	v_lshlrev_b32_e32 v148, 16, v27
	v_and_b32_e32 v149, 0xffff0000, v27
	v_lshlrev_b32_e32 v150, 16, v28
	v_and_b32_e32 v151, 0xffff0000, v28
	v_lshlrev_b32_e32 v152, 16, v29
	v_and_b32_e32 v153, 0xffff0000, v29
	s_setprio 3
	ds_read_b32 v240, v217 offset:35376
	v_lshlrev_b32_e32 v245, 2, v124
	v_add_u32_e32 v245, 0xb800, v245
	v_add_u32_e32 v227, 0x8a00, v217
	s_movk_i32 s0, 0x200
	s_mov_b32 s2, 0
	v_cndmask_b32_e64 v244, v245, v221, s[44:45]
	s_waitcnt lgkmcnt(0)
	ds_read_b32 v241, v227 offset:64
	s_waitcnt vmcnt(5)
	v_mad_u64_u32 v[242:243], s[6:7], v240, s0, v[84:85]
	global_load_dwordx4 v[30:33], v[242:243], off
	global_load_dwordx4 v[26:29], v[242:243], off offset:256
	v_cvt_scalef32_pk_f32_fp4 v[196:197], v66, 1.0
	v_cvt_scalef32_pk_f32_fp4 v[198:199], v66, 1.0 op_sel:[1,0,0]
	v_cvt_scalef32_pk_f32_fp4 v[230:231], v66, 1.0 op_sel:[0,1,0]
	v_cvt_scalef32_pk_f32_fp4 v[232:233], v66, 1.0 op_sel:[1,1,0]
	v_pk_fma_f32 v[234:235], v[112:113], v[196:197], 0 op_sel_hi:[1,1,0]
	v_pk_fma_f32 v[236:237], v[54:55], v[198:199], 0 op_sel_hi:[1,1,0]
	v_pk_fma_f32 v[234:235], v[114:115], v[230:231], v[234:235]
	v_pk_fma_f32 v[236:237], v[56:57], v[232:233], v[236:237]
	v_cvt_scalef32_pk_f32_fp4 v[196:197], v67, 1.0
	v_cvt_scalef32_pk_f32_fp4 v[198:199], v67, 1.0 op_sel:[1,0,0]
	v_cvt_scalef32_pk_f32_fp4 v[230:231], v67, 1.0 op_sel:[0,1,0]
	v_cvt_scalef32_pk_f32_fp4 v[232:233], v67, 1.0 op_sel:[1,1,0]
	v_pk_fma_f32 v[234:235], v[116:117], v[196:197], v[234:235]
	v_pk_fma_f32 v[236:237], v[50:51], v[198:199], v[236:237]
	v_pk_fma_f32 v[234:235], v[118:119], v[230:231], v[234:235]
	v_pk_fma_f32 v[236:237], v[52:53], v[232:233], v[236:237]
	v_cvt_scalef32_pk_f32_fp4 v[196:197], v68, 1.0
	v_cvt_scalef32_pk_f32_fp4 v[198:199], v68, 1.0 op_sel:[1,0,0]
	v_cvt_scalef32_pk_f32_fp4 v[230:231], v68, 1.0 op_sel:[0,1,0]
	v_cvt_scalef32_pk_f32_fp4 v[232:233], v68, 1.0 op_sel:[1,1,0]
	v_pk_fma_f32 v[234:235], v[120:121], v[196:197], v[234:235]
	v_pk_fma_f32 v[236:237], v[46:47], v[198:199], v[236:237]
	v_pk_fma_f32 v[234:235], v[122:123], v[230:231], v[234:235]
	v_pk_fma_f32 v[236:237], v[48:49], v[232:233], v[236:237]
	v_cvt_scalef32_pk_f32_fp4 v[196:197], v69, 1.0
	v_cvt_scalef32_pk_f32_fp4 v[198:199], v69, 1.0 op_sel:[1,0,0]
	v_cvt_scalef32_pk_f32_fp4 v[230:231], v69, 1.0 op_sel:[0,1,0]
	v_cvt_scalef32_pk_f32_fp4 v[232:233], v69, 1.0 op_sel:[1,1,0]
	v_pk_fma_f32 v[234:235], v[126:127], v[196:197], v[234:235]
	v_pk_fma_f32 v[236:237], v[38:39], v[198:199], v[236:237]
	v_pk_fma_f32 v[234:235], v[128:129], v[230:231], v[234:235]
	v_pk_fma_f32 v[236:237], v[40:41], v[232:233], v[236:237]
	s_waitcnt vmcnt(6)
	v_cvt_scalef32_pk_f32_fp4 v[196:197], v58, 1.0
	v_cvt_scalef32_pk_f32_fp4 v[198:199], v58, 1.0 op_sel:[1,0,0]
	v_cvt_scalef32_pk_f32_fp4 v[230:231], v58, 1.0 op_sel:[0,1,0]
	v_cvt_scalef32_pk_f32_fp4 v[232:233], v58, 1.0 op_sel:[1,1,0]
	v_pk_fma_f32 v[234:235], v[130:131], v[196:197], v[234:235]
	v_pk_fma_f32 v[236:237], v[42:43], v[198:199], v[236:237]
	v_pk_fma_f32 v[234:235], v[132:133], v[230:231], v[234:235]
	v_pk_fma_f32 v[236:237], v[44:45], v[232:233], v[236:237]
	v_cvt_scalef32_pk_f32_fp4 v[196:197], v59, 1.0
	v_cvt_scalef32_pk_f32_fp4 v[198:199], v59, 1.0 op_sel:[1,0,0]
	v_cvt_scalef32_pk_f32_fp4 v[230:231], v59, 1.0 op_sel:[0,1,0]
	v_cvt_scalef32_pk_f32_fp4 v[232:233], v59, 1.0 op_sel:[1,1,0]
	v_pk_fma_f32 v[234:235], v[134:135], v[196:197], v[234:235]
	v_pk_fma_f32 v[236:237], v[34:35], v[198:199], v[236:237]
	v_pk_fma_f32 v[234:235], v[136:137], v[230:231], v[234:235]
	v_pk_fma_f32 v[236:237], v[36:37], v[232:233], v[236:237]
	v_cvt_scalef32_pk_f32_fp4 v[196:197], v60, 1.0
	v_cvt_scalef32_pk_f32_fp4 v[198:199], v60, 1.0 op_sel:[1,0,0]
	v_cvt_scalef32_pk_f32_fp4 v[230:231], v60, 1.0 op_sel:[0,1,0]
	v_cvt_scalef32_pk_f32_fp4 v[232:233], v60, 1.0 op_sel:[1,1,0]
	v_pk_fma_f32 v[234:235], v[138:139], v[196:197], v[234:235]
	v_pk_fma_f32 v[236:237], v[140:141], v[198:199], v[236:237]
	v_pk_fma_f32 v[234:235], v[142:143], v[230:231], v[234:235]
	v_pk_fma_f32 v[236:237], v[144:145], v[232:233], v[236:237]
	v_cvt_scalef32_pk_f32_fp4 v[196:197], v61, 1.0
	v_cvt_scalef32_pk_f32_fp4 v[198:199], v61, 1.0 op_sel:[1,0,0]
	v_cvt_scalef32_pk_f32_fp4 v[230:231], v61, 1.0 op_sel:[0,1,0]
	v_cvt_scalef32_pk_f32_fp4 v[232:233], v61, 1.0 op_sel:[1,1,0]
	v_pk_fma_f32 v[234:235], v[146:147], v[196:197], v[234:235]
	v_pk_fma_f32 v[236:237], v[148:149], v[198:199], v[236:237]
	v_pk_fma_f32 v[234:235], v[150:151], v[230:231], v[234:235]
	v_pk_fma_f32 v[236:237], v[152:153], v[232:233], v[236:237]
	v_add_f32_e32 v238, v236, v237
	v_add_f32_e32 v242, v234, v235
	v_add_f32_e32 v238, v242, v238
	s_waitcnt lgkmcnt(0)
	s_nop 0
	v_add_f32_dpp v238, v238, v238 quad_perm:[1,0,3,2] row_mask:0xf bank_mask:0xf bound_ctrl:1
	ds_read_b32 v240, v227 offset:80
	s_waitcnt vmcnt(5)
	v_add_f32_dpp v238, v238, v238 quad_perm:[2,3,0,1] row_mask:0xf bank_mask:0xf bound_ctrl:1
	v_mad_u64_u32 v[242:243], s[6:7], v241, s0, v[84:85]
	global_load_dwordx4 v[66:69], v[242:243], off
	v_add_f32_dpp v238, v238, v238 row_half_mirror row_mask:0xf bank_mask:0xf bound_ctrl:1
	global_load_dwordx4 v[58:61], v[242:243], off offset:256
	s_nop 0
	v_add_f32_dpp v238, v238, v238 row_mirror row_mask:0xf bank_mask:0xf bound_ctrl:1
	ds_write_b32 v244, v238 offset:0

.Lpv_loop:
	v_mad_u64_u32 v[248:249], vcc, v227, s0, v[86:87]
	global_load_dwordx4 v[10:13], v[248:249], off
	global_load_dwordx4 v[2:5], v[248:249], off offset:256
	ds_read_b32 v250, v131 offset:16
	ds_read_b32 v130, v132 offset:16
	s_waitcnt vmcnt(15)
	v_cvt_scalef32_pk_f32_fp4 v[134:135], v14, 1.0
	v_cvt_scalef32_pk_f32_fp4 v[136:137], v14, 1.0 op_sel:[1,0,0]
	v_cvt_scalef32_pk_f32_fp4 v[138:139], v14, 1.0 op_sel:[0,1,0]
	v_cvt_scalef32_pk_f32_fp4 v[140:141], v14, 1.0 op_sel:[1,1,0]
	s_waitcnt lgkmcnt(0)
	v_pk_fma_f32 v[128:129], v[130:131], v[134:135], v[128:129] op_sel_hi:[0,1,1]
	v_pk_fma_f32 v[126:127], v[130:131], v[136:137], v[126:127] op_sel_hi:[0,1,1]
	v_pk_fma_f32 v[122:123], v[130:131], v[138:139], v[122:123] op_sel_hi:[0,1,1]
	v_pk_fma_f32 v[120:121], v[130:131], v[140:141], v[120:121] op_sel_hi:[0,1,1]
	v_cvt_scalef32_pk_f32_fp4 v[134:135], v15, 1.0
	v_cvt_scalef32_pk_f32_fp4 v[136:137], v15, 1.0 op_sel:[1,0,0]
	v_cvt_scalef32_pk_f32_fp4 v[138:139], v15, 1.0 op_sel:[0,1,0]
	v_cvt_scalef32_pk_f32_fp4 v[140:141], v15, 1.0 op_sel:[1,1,0]
	v_pk_fma_f32 v[118:119], v[130:131], v[134:135], v[118:119] op_sel_hi:[0,1,1]
	v_pk_fma_f32 v[116:117], v[130:131], v[136:137], v[116:117] op_sel_hi:[0,1,1]
	v_pk_fma_f32 v[114:115], v[130:131], v[138:139], v[114:115] op_sel_hi:[0,1,1]
	v_pk_fma_f32 v[112:113], v[130:131], v[140:141], v[112:113] op_sel_hi:[0,1,1]
	v_cvt_scalef32_pk_f32_fp4 v[134:135], v16, 1.0
	v_cvt_scalef32_pk_f32_fp4 v[136:137], v16, 1.0 op_sel:[1,0,0]
	v_cvt_scalef32_pk_f32_fp4 v[138:139], v16, 1.0 op_sel:[0,1,0]
	v_cvt_scalef32_pk_f32_fp4 v[140:141], v16, 1.0 op_sel:[1,1,0]
	v_pk_fma_f32 v[80:81], v[130:131], v[134:135], v[80:81] op_sel_hi:[0,1,1]
	v_pk_fma_f32 v[78:79], v[130:131], v[136:137], v[78:79] op_sel_hi:[0,1,1]
	v_pk_fma_f32 v[76:77], v[130:131], v[138:139], v[76:77] op_sel_hi:[0,1,1]
	v_pk_fma_f32 v[74:75], v[130:131], v[140:141], v[74:75] op_sel_hi:[0,1,1]
	v_cvt_scalef32_pk_f32_fp4 v[134:135], v17, 1.0
	v_cvt_scalef32_pk_f32_fp4 v[136:137], v17, 1.0 op_sel:[1,0,0]
	v_cvt_scalef32_pk_f32_fp4 v[138:139], v17, 1.0 op_sel:[0,1,0]
	v_cvt_scalef32_pk_f32_fp4 v[140:141], v17, 1.0 op_sel:[1,1,0]
	v_pk_fma_f32 v[72:73], v[130:131], v[134:135], v[72:73] op_sel_hi:[0,1,1]
	v_pk_fma_f32 v[70:71], v[130:131], v[136:137], v[70:71] op_sel_hi:[0,1,1]
	v_pk_fma_f32 v[68:69], v[130:131], v[138:139], v[68:69] op_sel_hi:[0,1,1]
	v_pk_fma_f32 v[66:67], v[130:131], v[140:141], v[66:67] op_sel_hi:[0,1,1]
	s_waitcnt vmcnt(14)
	v_cvt_scalef32_pk_f32_fp4 v[134:135], v6, 1.0
	v_cvt_scalef32_pk_f32_fp4 v[136:137], v6, 1.0 op_sel:[1,0,0]
	v_cvt_scalef32_pk_f32_fp4 v[138:139], v6, 1.0 op_sel:[0,1,0]
	v_cvt_scalef32_pk_f32_fp4 v[140:141], v6, 1.0 op_sel:[1,1,0]
	v_pk_fma_f32 v[34:35], v[130:131], v[134:135], v[34:35] op_sel_hi:[0,1,1]
	v_pk_fma_f32 v[36:37], v[130:131], v[136:137], v[36:37] op_sel_hi:[0,1,1]
	v_pk_fma_f32 v[38:39], v[130:131], v[138:139], v[38:39] op_sel_hi:[0,1,1]
	v_pk_fma_f32 v[40:41], v[130:131], v[140:141], v[40:41] op_sel_hi:[0,1,1]
	v_cvt_scalef32_pk_f32_fp4 v[134:135], v7, 1.0
	v_cvt_scalef32_pk_f32_fp4 v[136:137], v7, 1.0 op_sel:[1,0,0]
	v_cvt_scalef32_pk_f32_fp4 v[138:139], v7, 1.0 op_sel:[0,1,0]
	v_cvt_scalef32_pk_f32_fp4 v[140:141], v7, 1.0 op_sel:[1,1,0]
	v_pk_fma_f32 v[42:43], v[130:131], v[134:135], v[42:43] op_sel_hi:[0,1,1]
	v_pk_fma_f32 v[44:45], v[130:131], v[136:137], v[44:45] op_sel_hi:[0,1,1]
	v_pk_fma_f32 v[46:47], v[130:131], v[138:139], v[46:47] op_sel_hi:[0,1,1]
	v_pk_fma_f32 v[48:49], v[130:131], v[140:141], v[48:49] op_sel_hi:[0,1,1]
	v_cvt_scalef32_pk_f32_fp4 v[134:135], v8, 1.0
	v_cvt_scalef32_pk_f32_fp4 v[136:137], v8, 1.0 op_sel:[1,0,0]
	v_cvt_scalef32_pk_f32_fp4 v[138:139], v8, 1.0 op_sel:[0,1,0]
	v_cvt_scalef32_pk_f32_fp4 v[140:141], v8, 1.0 op_sel:[1,1,0]
	v_pk_fma_f32 v[50:51], v[130:131], v[134:135], v[50:51] op_sel_hi:[0,1,1]
	v_pk_fma_f32 v[52:53], v[130:131], v[136:137], v[52:53] op_sel_hi:[0,1,1]
	v_pk_fma_f32 v[54:55], v[130:131], v[138:139], v[54:55] op_sel_hi:[0,1,1]
	v_pk_fma_f32 v[56:57], v[130:131], v[140:141], v[56:57] op_sel_hi:[0,1,1]
	v_cvt_scalef32_pk_f32_fp4 v[134:135], v9, 1.0
	v_cvt_scalef32_pk_f32_fp4 v[136:137], v9, 1.0 op_sel:[1,0,0]
	v_cvt_scalef32_pk_f32_fp4 v[138:139], v9, 1.0 op_sel:[0,1,0]
	v_cvt_scalef32_pk_f32_fp4 v[140:141], v9, 1.0 op_sel:[1,1,0]
	v_pk_fma_f32 v[58:59], v[130:131], v[134:135], v[58:59] op_sel_hi:[0,1,1]
	v_pk_fma_f32 v[60:61], v[130:131], v[136:137], v[60:61] op_sel_hi:[0,1,1]
	v_pk_fma_f32 v[62:63], v[130:131], v[138:139], v[62:63] op_sel_hi:[0,1,1]
	v_pk_fma_f32 v[64:65], v[130:131], v[140:141], v[64:65] op_sel_hi:[0,1,1]
	v_mad_u64_u32 v[248:249], vcc, v250, s0, v[86:87]
	global_load_dwordx4 v[14:17], v[248:249], off
	global_load_dwordx4 v[6:9], v[248:249], off offset:256
	ds_read_b32 v227, v131 offset:32
	ds_read_b32 v130, v132 offset:32
	s_waitcnt vmcnt(15)
	v_cvt_scalef32_pk_f32_fp4 v[134:135], v22, 1.0
	v_cvt_scalef32_pk_f32_fp4 v[136:137], v22, 1.0 op_sel:[1,0,0]
	v_cvt_scalef32_pk_f32_fp4 v[138:139], v22, 1.0 op_sel:[0,1,0]
	v_cvt_scalef32_pk_f32_fp4 v[140:141], v22, 1.0 op_sel:[1,1,0]
	s_waitcnt lgkmcnt(0)
	v_pk_fma_f32 v[128:129], v[130:131], v[134:135], v[128:129] op_sel_hi:[0,1,1]
	v_pk_fma_f32 v[126:127], v[130:131], v[136:137], v[126:127] op_sel_hi:[0,1,1]
	v_pk_fma_f32 v[122:123], v[130:131], v[138:139], v[122:123] op_sel_hi:[0,1,1]
	v_pk_fma_f32 v[120:121], v[130:131], v[140:141], v[120:121] op_sel_hi:[0,1,1]
	v_cvt_scalef32_pk_f32_fp4 v[134:135], v23, 1.0
	v_cvt_scalef32_pk_f32_fp4 v[136:137], v23, 1.0 op_sel:[1,0,0]
	v_cvt_scalef32_pk_f32_fp4 v[138:139], v23, 1.0 op_sel:[0,1,0]
	v_cvt_scalef32_pk_f32_fp4 v[140:141], v23, 1.0 op_sel:[1,1,0]
	v_pk_fma_f32 v[118:119], v[130:131], v[134:135], v[118:119] op_sel_hi:[0,1,1]
	v_pk_fma_f32 v[116:117], v[130:131], v[136:137], v[116:117] op_sel_hi:[0,1,1]
	v_pk_fma_f32 v[114:115], v[130:131], v[138:139], v[114:115] op_sel_hi:[0,1,1]
	v_pk_fma_f32 v[112:113], v[130:131], v[140:141], v[112:113] op_sel_hi:[0,1,1]
	v_cvt_scalef32_pk_f32_fp4 v[134:135], v24, 1.0
	v_cvt_scalef32_pk_f32_fp4 v[136:137], v24, 1.0 op_sel:[1,0,0]
	v_cvt_scalef32_pk_f32_fp4 v[138:139], v24, 1.0 op_sel:[0,1,0]
	v_cvt_scalef32_pk_f32_fp4 v[140:141], v24, 1.0 op_sel:[1,1,0]
	v_pk_fma_f32 v[80:81], v[130:131], v[134:135], v[80:81] op_sel_hi:[0,1,1]
	v_pk_fma_f32 v[78:79], v[130:131], v[136:137], v[78:79] op_sel_hi:[0,1,1]
	v_pk_fma_f32 v[76:77], v[130:131], v[138:139], v[76:77] op_sel_hi:[0,1,1]
	v_pk_fma_f32 v[74:75], v[130:131], v[140:141], v[74:75] op_sel_hi:[0,1,1]
	v_cvt_scalef32_pk_f32_fp4 v[134:135], v25, 1.0
	v_cvt_scalef32_pk_f32_fp4 v[136:137], v25, 1.0 op_sel:[1,0,0]
	v_cvt_scalef32_pk_f32_fp4 v[138:139], v25, 1.0 op_sel:[0,1,0]
	v_cvt_scalef32_pk_f32_fp4 v[140:141], v25, 1.0 op_sel:[1,1,0]
	v_pk_fma_f32 v[72:73], v[130:131], v[134:135], v[72:73] op_sel_hi:[0,1,1]
	v_pk_fma_f32 v[70:71], v[130:131], v[136:137], v[70:71] op_sel_hi:[0,1,1]
	v_pk_fma_f32 v[68:69], v[130:131], v[138:139], v[68:69] op_sel_hi:[0,1,1]
	v_pk_fma_f32 v[66:67], v[130:131], v[140:141], v[66:67] op_sel_hi:[0,1,1]
	s_waitcnt vmcnt(14)
	v_cvt_scalef32_pk_f32_fp4 v[134:135], v18, 1.0
	v_cvt_scalef32_pk_f32_fp4 v[136:137], v18, 1.0 op_sel:[1,0,0]
	v_cvt_scalef32_pk_f32_fp4 v[138:139], v18, 1.0 op_sel:[0,1,0]
	v_cvt_scalef32_pk_f32_fp4 v[140:141], v18, 1.0 op_sel:[1,1,0]
	v_pk_fma_f32 v[34:35], v[130:131], v[134:135], v[34:35] op_sel_hi:[0,1,1]
	v_pk_fma_f32 v[36:37], v[130:131], v[136:137], v[36:37] op_sel_hi:[0,1,1]
	v_pk_fma_f32 v[38:39], v[130:131], v[138:139], v[38:39] op_sel_hi:[0,1,1]
	v_pk_fma_f32 v[40:41], v[130:131], v[140:141], v[40:41] op_sel_hi:[0,1,1]
	v_cvt_scalef32_pk_f32_fp4 v[134:135], v19, 1.0
	v_cvt_scalef32_pk_f32_fp4 v[136:137], v19, 1.0 op_sel:[1,0,0]
	v_cvt_scalef32_pk_f32_fp4 v[138:139], v19, 1.0 op_sel:[0,1,0]
	v_cvt_scalef32_pk_f32_fp4 v[140:141], v19, 1.0 op_sel:[1,1,0]
	v_pk_fma_f32 v[42:43], v[130:131], v[134:135], v[42:43] op_sel_hi:[0,1,1]
	v_pk_fma_f32 v[44:45], v[130:131], v[136:137], v[44:45] op_sel_hi:[0,1,1]
	v_pk_fma_f32 v[46:47], v[130:131], v[138:139], v[46:47] op_sel_hi:[0,1,1]
	v_pk_fma_f32 v[48:49], v[130:131], v[140:141], v[48:49] op_sel_hi:[0,1,1]
	v_cvt_scalef32_pk_f32_fp4 v[134:135], v20, 1.0
	v_cvt_scalef32_pk_f32_fp4 v[136:137], v20, 1.0 op_sel:[1,0,0]
	v_cvt_scalef32_pk_f32_fp4 v[138:139], v20, 1.0 op_sel:[0,1,0]
	v_cvt_scalef32_pk_f32_fp4 v[140:141], v20, 1.0 op_sel:[1,1,0]
	v_pk_fma_f32 v[50:51], v[130:131], v[134:135], v[50:51] op_sel_hi:[0,1,1]
	v_pk_fma_f32 v[52:53], v[130:131], v[136:137], v[52:53] op_sel_hi:[0,1,1]
	v_pk_fma_f32 v[54:55], v[130:131], v[138:139], v[54:55] op_sel_hi:[0,1,1]
	v_pk_fma_f32 v[56:57], v[130:131], v[140:141], v[56:57] op_sel_hi:[0,1,1]
	v_cvt_scalef32_pk_f32_fp4 v[134:135], v21, 1.0
	v_cvt_scalef32_pk_f32_fp4 v[136:137], v21, 1.0 op_sel:[1,0,0]
	v_cvt_scalef32_pk_f32_fp4 v[138:139], v21, 1.0 op_sel:[0,1,0]
	v_cvt_scalef32_pk_f32_fp4 v[140:141], v21, 1.0 op_sel:[1,1,0]
	v_pk_fma_f32 v[58:59], v[130:131], v[134:135], v[58:59] op_sel_hi:[0,1,1]
	v_pk_fma_f32 v[60:61], v[130:131], v[136:137], v[60:61] op_sel_hi:[0,1,1]
	v_pk_fma_f32 v[62:63], v[130:131], v[138:139], v[62:63] op_sel_hi:[0,1,1]
	v_pk_fma_f32 v[64:65], v[130:131], v[140:141], v[64:65] op_sel_hi:[0,1,1]
	v_mad_u64_u32 v[248:249], vcc, v227, s0, v[86:87]
	global_load_dwordx4 v[22:25], v[248:249], off
	global_load_dwordx4 v[18:21], v[248:249], off offset:256
	ds_read_b32 v250, v131 offset:48
	ds_read_b32 v130, v132 offset:48
	s_waitcnt vmcnt(15)
	v_cvt_scalef32_pk_f32_fp4 v[134:135], v30, 1.0
	v_cvt_scalef32_pk_f32_fp4 v[136:137], v30, 1.0 op_sel:[1,0,0]
	v_cvt_scalef32_pk_f32_fp4 v[138:139], v30, 1.0 op_sel:[0,1,0]
	v_cvt_scalef32_pk_f32_fp4 v[140:141], v30, 1.0 op_sel:[1,1,0]
	s_waitcnt lgkmcnt(0)
	v_pk_fma_f32 v[128:129], v[130:131], v[134:135], v[128:129] op_sel_hi:[0,1,1]
	v_pk_fma_f32 v[126:127], v[130:131], v[136:137], v[126:127] op_sel_hi:[0,1,1]
	v_pk_fma_f32 v[122:123], v[130:131], v[138:139], v[122:123] op_sel_hi:[0,1,1]
	v_pk_fma_f32 v[120:121], v[130:131], v[140:141], v[120:121] op_sel_hi:[0,1,1]
	v_cvt_scalef32_pk_f32_fp4 v[134:135], v31, 1.0
	v_cvt_scalef32_pk_f32_fp4 v[136:137], v31, 1.0 op_sel:[1,0,0]
	v_cvt_scalef32_pk_f32_fp4 v[138:139], v31, 1.0 op_sel:[0,1,0]
	v_cvt_scalef32_pk_f32_fp4 v[140:141], v31, 1.0 op_sel:[1,1,0]
	v_pk_fma_f32 v[118:119], v[130:131], v[134:135], v[118:119] op_sel_hi:[0,1,1]
	v_pk_fma_f32 v[116:117], v[130:131], v[136:137], v[116:117] op_sel_hi:[0,1,1]
	v_pk_fma_f32 v[114:115], v[130:131], v[138:139], v[114:115] op_sel_hi:[0,1,1]
	v_pk_fma_f32 v[112:113], v[130:131], v[140:141], v[112:113] op_sel_hi:[0,1,1]
	v_cvt_scalef32_pk_f32_fp4 v[134:135], v32, 1.0
	v_cvt_scalef32_pk_f32_fp4 v[136:137], v32, 1.0 op_sel:[1,0,0]
	v_cvt_scalef32_pk_f32_fp4 v[138:139], v32, 1.0 op_sel:[0,1,0]
	v_cvt_scalef32_pk_f32_fp4 v[140:141], v32, 1.0 op_sel:[1,1,0]
	v_pk_fma_f32 v[80:81], v[130:131], v[134:135], v[80:81] op_sel_hi:[0,1,1]
	v_pk_fma_f32 v[78:79], v[130:131], v[136:137], v[78:79] op_sel_hi:[0,1,1]
	v_pk_fma_f32 v[76:77], v[130:131], v[138:139], v[76:77] op_sel_hi:[0,1,1]
	v_pk_fma_f32 v[74:75], v[130:131], v[140:141], v[74:75] op_sel_hi:[0,1,1]
	v_cvt_scalef32_pk_f32_fp4 v[134:135], v33, 1.0
	v_cvt_scalef32_pk_f32_fp4 v[136:137], v33, 1.0 op_sel:[1,0,0]
	v_cvt_scalef32_pk_f32_fp4 v[138:139], v33, 1.0 op_sel:[0,1,0]
	v_cvt_scalef32_pk_f32_fp4 v[140:141], v33, 1.0 op_sel:[1,1,0]
	v_pk_fma_f32 v[72:73], v[130:131], v[134:135], v[72:73] op_sel_hi:[0,1,1]
	v_pk_fma_f32 v[70:71], v[130:131], v[136:137], v[70:71] op_sel_hi:[0,1,1]
	v_pk_fma_f32 v[68:69], v[130:131], v[138:139], v[68:69] op_sel_hi:[0,1,1]
	v_pk_fma_f32 v[66:67], v[130:131], v[140:141], v[66:67] op_sel_hi:[0,1,1]
	s_waitcnt vmcnt(14)
	v_cvt_scalef32_pk_f32_fp4 v[134:135], v26, 1.0
	v_cvt_scalef32_pk_f32_fp4 v[136:137], v26, 1.0 op_sel:[1,0,0]
	v_cvt_scalef32_pk_f32_fp4 v[138:139], v26, 1.0 op_sel:[0,1,0]
	v_cvt_scalef32_pk_f32_fp4 v[140:141], v26, 1.0 op_sel:[1,1,0]
	v_pk_fma_f32 v[34:35], v[130:131], v[134:135], v[34:35] op_sel_hi:[0,1,1]
	v_pk_fma_f32 v[36:37], v[130:131], v[136:137], v[36:37] op_sel_hi:[0,1,1]
	v_pk_fma_f32 v[38:39], v[130:131], v[138:139], v[38:39] op_sel_hi:[0,1,1]
	v_pk_fma_f32 v[40:41], v[130:131], v[140:141], v[40:41] op_sel_hi:[0,1,1]
	v_cvt_scalef32_pk_f32_fp4 v[134:135], v27, 1.0
	v_cvt_scalef32_pk_f32_fp4 v[136:137], v27, 1.0 op_sel:[1,0,0]
	v_cvt_scalef32_pk_f32_fp4 v[138:139], v27, 1.0 op_sel:[0,1,0]
	v_cvt_scalef32_pk_f32_fp4 v[140:141], v27, 1.0 op_sel:[1,1,0]
	v_pk_fma_f32 v[42:43], v[130:131], v[134:135], v[42:43] op_sel_hi:[0,1,1]
	v_pk_fma_f32 v[44:45], v[130:131], v[136:137], v[44:45] op_sel_hi:[0,1,1]
	v_pk_fma_f32 v[46:47], v[130:131], v[138:139], v[46:47] op_sel_hi:[0,1,1]
	v_pk_fma_f32 v[48:49], v[130:131], v[140:141], v[48:49] op_sel_hi:[0,1,1]
	v_cvt_scalef32_pk_f32_fp4 v[134:135], v28, 1.0
	v_cvt_scalef32_pk_f32_fp4 v[136:137], v28, 1.0 op_sel:[1,0,0]
	v_cvt_scalef32_pk_f32_fp4 v[138:139], v28, 1.0 op_sel:[0,1,0]
	v_cvt_scalef32_pk_f32_fp4 v[140:141], v28, 1.0 op_sel:[1,1,0]
	v_pk_fma_f32 v[50:51], v[130:131], v[134:135], v[50:51] op_sel_hi:[0,1,1]
	v_pk_fma_f32 v[52:53], v[130:131], v[136:137], v[52:53] op_sel_hi:[0,1,1]
	v_pk_fma_f32 v[54:55], v[130:131], v[138:139], v[54:55] op_sel_hi:[0,1,1]
	v_pk_fma_f32 v[56:57], v[130:131], v[140:141], v[56:57] op_sel_hi:[0,1,1]
	v_cvt_scalef32_pk_f32_fp4 v[134:135], v29, 1.0
	v_cvt_scalef32_pk_f32_fp4 v[136:137], v29, 1.0 op_sel:[1,0,0]
	v_cvt_scalef32_pk_f32_fp4 v[138:139], v29, 1.0 op_sel:[0,1,0]
	v_cvt_scalef32_pk_f32_fp4 v[140:141], v29, 1.0 op_sel:[1,1,0]
	v_pk_fma_f32 v[58:59], v[130:131], v[134:135], v[58:59] op_sel_hi:[0,1,1]
	v_pk_fma_f32 v[60:61], v[130:131], v[136:137], v[60:61] op_sel_hi:[0,1,1]
	v_pk_fma_f32 v[62:63], v[130:131], v[138:139], v[62:63] op_sel_hi:[0,1,1]
	v_pk_fma_f32 v[64:65], v[130:131], v[140:141], v[64:65] op_sel_hi:[0,1,1]
	v_mad_u64_u32 v[248:249], vcc, v250, s0, v[86:87]
	global_load_dwordx4 v[30:33], v[248:249], off
	global_load_dwordx4 v[26:29], v[248:249], off offset:256
	ds_read_b32 v227, v131 offset:64
	ds_read_b32 v130, v132 offset:64
	s_waitcnt vmcnt(15)
	v_cvt_scalef32_pk_f32_fp4 v[134:135], v142, 1.0
	v_cvt_scalef32_pk_f32_fp4 v[136:137], v142, 1.0 op_sel:[1,0,0]
	v_cvt_scalef32_pk_f32_fp4 v[138:139], v142, 1.0 op_sel:[0,1,0]
	v_cvt_scalef32_pk_f32_fp4 v[140:141], v142, 1.0 op_sel:[1,1,0]
	s_waitcnt lgkmcnt(0)
	v_pk_fma_f32 v[128:129], v[130:131], v[134:135], v[128:129] op_sel_hi:[0,1,1]
	v_pk_fma_f32 v[126:127], v[130:131], v[136:137], v[126:127] op_sel_hi:[0,1,1]
	v_pk_fma_f32 v[122:123], v[130:131], v[138:139], v[122:123] op_sel_hi:[0,1,1]
	v_pk_fma_f32 v[120:121], v[130:131], v[140:141], v[120:121] op_sel_hi:[0,1,1]
	v_cvt_scalef32_pk_f32_fp4 v[134:135], v143, 1.0
	v_cvt_scalef32_pk_f32_fp4 v[136:137], v143, 1.0 op_sel:[1,0,0]
	v_cvt_scalef32_pk_f32_fp4 v[138:139], v143, 1.0 op_sel:[0,1,0]
	v_cvt_scalef32_pk_f32_fp4 v[140:141], v143, 1.0 op_sel:[1,1,0]
	v_pk_fma_f32 v[118:119], v[130:131], v[134:135], v[118:119] op_sel_hi:[0,1,1]
	v_pk_fma_f32 v[116:117], v[130:131], v[136:137], v[116:117] op_sel_hi:[0,1,1]
	v_pk_fma_f32 v[114:115], v[130:131], v[138:139], v[114:115] op_sel_hi:[0,1,1]
	v_pk_fma_f32 v[112:113], v[130:131], v[140:141], v[112:113] op_sel_hi:[0,1,1]
	v_cvt_scalef32_pk_f32_fp4 v[134:135], v144, 1.0
	v_cvt_scalef32_pk_f32_fp4 v[136:137], v144, 1.0 op_sel:[1,0,0]
	v_cvt_scalef32_pk_f32_fp4 v[138:139], v144, 1.0 op_sel:[0,1,0]
	v_cvt_scalef32_pk_f32_fp4 v[140:141], v144, 1.0 op_sel:[1,1,0]
	v_pk_fma_f32 v[80:81], v[130:131], v[134:135], v[80:81] op_sel_hi:[0,1,1]
	v_pk_fma_f32 v[78:79], v[130:131], v[136:137], v[78:79] op_sel_hi:[0,1,1]
	v_pk_fma_f32 v[76:77], v[130:131], v[138:139], v[76:77] op_sel_hi:[0,1,1]
	v_pk_fma_f32 v[74:75], v[130:131], v[140:141], v[74:75] op_sel_hi:[0,1,1]
	v_cvt_scalef32_pk_f32_fp4 v[134:135], v145, 1.0
	v_cvt_scalef32_pk_f32_fp4 v[136:137], v145, 1.0 op_sel:[1,0,0]
	v_cvt_scalef32_pk_f32_fp4 v[138:139], v145, 1.0 op_sel:[0,1,0]
	v_cvt_scalef32_pk_f32_fp4 v[140:141], v145, 1.0 op_sel:[1,1,0]
	v_pk_fma_f32 v[72:73], v[130:131], v[134:135], v[72:73] op_sel_hi:[0,1,1]
	v_pk_fma_f32 v[70:71], v[130:131], v[136:137], v[70:71] op_sel_hi:[0,1,1]
	v_pk_fma_f32 v[68:69], v[130:131], v[138:139], v[68:69] op_sel_hi:[0,1,1]
	v_pk_fma_f32 v[66:67], v[130:131], v[140:141], v[66:67] op_sel_hi:[0,1,1]
	s_waitcnt vmcnt(14)
	v_cvt_scalef32_pk_f32_fp4 v[134:135], v146, 1.0
	v_cvt_scalef32_pk_f32_fp4 v[136:137], v146, 1.0 op_sel:[1,0,0]
	v_cvt_scalef32_pk_f32_fp4 v[138:139], v146, 1.0 op_sel:[0,1,0]
	v_cvt_scalef32_pk_f32_fp4 v[140:141], v146, 1.0 op_sel:[1,1,0]
	v_pk_fma_f32 v[34:35], v[130:131], v[134:135], v[34:35] op_sel_hi:[0,1,1]
	v_pk_fma_f32 v[36:37], v[130:131], v[136:137], v[36:37] op_sel_hi:[0,1,1]
	v_pk_fma_f32 v[38:39], v[130:131], v[138:139], v[38:39] op_sel_hi:[0,1,1]
	v_pk_fma_f32 v[40:41], v[130:131], v[140:141], v[40:41] op_sel_hi:[0,1,1]
	v_cvt_scalef32_pk_f32_fp4 v[134:135], v147, 1.0
	v_cvt_scalef32_pk_f32_fp4 v[136:137], v147, 1.0 op_sel:[1,0,0]
	v_cvt_scalef32_pk_f32_fp4 v[138:139], v147, 1.0 op_sel:[0,1,0]
	v_cvt_scalef32_pk_f32_fp4 v[140:141], v147, 1.0 op_sel:[1,1,0]
	v_pk_fma_f32 v[42:43], v[130:131], v[134:135], v[42:43] op_sel_hi:[0,1,1]
	v_pk_fma_f32 v[44:45], v[130:131], v[136:137], v[44:45] op_sel_hi:[0,1,1]
	v_pk_fma_f32 v[46:47], v[130:131], v[138:139], v[46:47] op_sel_hi:[0,1,1]
	v_pk_fma_f32 v[48:49], v[130:131], v[140:141], v[48:49] op_sel_hi:[0,1,1]
	v_cvt_scalef32_pk_f32_fp4 v[134:135], v148, 1.0
	v_cvt_scalef32_pk_f32_fp4 v[136:137], v148, 1.0 op_sel:[1,0,0]
	v_cvt_scalef32_pk_f32_fp4 v[138:139], v148, 1.0 op_sel:[0,1,0]
	v_cvt_scalef32_pk_f32_fp4 v[140:141], v148, 1.0 op_sel:[1,1,0]
	v_pk_fma_f32 v[50:51], v[130:131], v[134:135], v[50:51] op_sel_hi:[0,1,1]
	v_pk_fma_f32 v[52:53], v[130:131], v[136:137], v[52:53] op_sel_hi:[0,1,1]
	v_pk_fma_f32 v[54:55], v[130:131], v[138:139], v[54:55] op_sel_hi:[0,1,1]
	v_pk_fma_f32 v[56:57], v[130:131], v[140:141], v[56:57] op_sel_hi:[0,1,1]
	v_cvt_scalef32_pk_f32_fp4 v[134:135], v149, 1.0
	v_cvt_scalef32_pk_f32_fp4 v[136:137], v149, 1.0 op_sel:[1,0,0]
	v_cvt_scalef32_pk_f32_fp4 v[138:139], v149, 1.0 op_sel:[0,1,0]
	v_cvt_scalef32_pk_f32_fp4 v[140:141], v149, 1.0 op_sel:[1,1,0]
	v_pk_fma_f32 v[58:59], v[130:131], v[134:135], v[58:59] op_sel_hi:[0,1,1]
	v_pk_fma_f32 v[60:61], v[130:131], v[136:137], v[60:61] op_sel_hi:[0,1,1]
	v_pk_fma_f32 v[62:63], v[130:131], v[138:139], v[62:63] op_sel_hi:[0,1,1]
	v_pk_fma_f32 v[64:65], v[130:131], v[140:141], v[64:65] op_sel_hi:[0,1,1]
	v_mad_u64_u32 v[248:249], vcc, v227, s0, v[86:87]
	global_load_dwordx4 v[142:145], v[248:249], off
	global_load_dwordx4 v[146:149], v[248:249], off offset:256
	ds_read_b32 v250, v131 offset:80
	ds_read_b32 v130, v132 offset:80
	s_waitcnt vmcnt(15)
	v_cvt_scalef32_pk_f32_fp4 v[134:135], v150, 1.0
	v_cvt_scalef32_pk_f32_fp4 v[136:137], v150, 1.0 op_sel:[1,0,0]
	v_cvt_scalef32_pk_f32_fp4 v[138:139], v150, 1.0 op_sel:[0,1,0]
	v_cvt_scalef32_pk_f32_fp4 v[140:141], v150, 1.0 op_sel:[1,1,0]
	s_waitcnt lgkmcnt(0)
	v_pk_fma_f32 v[128:129], v[130:131], v[134:135], v[128:129] op_sel_hi:[0,1,1]
	v_pk_fma_f32 v[126:127], v[130:131], v[136:137], v[126:127] op_sel_hi:[0,1,1]
	v_pk_fma_f32 v[122:123], v[130:131], v[138:139], v[122:123] op_sel_hi:[0,1,1]
	v_pk_fma_f32 v[120:121], v[130:131], v[140:141], v[120:121] op_sel_hi:[0,1,1]
	v_cvt_scalef32_pk_f32_fp4 v[134:135], v151, 1.0
	v_cvt_scalef32_pk_f32_fp4 v[136:137], v151, 1.0 op_sel:[1,0,0]
	v_cvt_scalef32_pk_f32_fp4 v[138:139], v151, 1.0 op_sel:[0,1,0]
	v_cvt_scalef32_pk_f32_fp4 v[140:141], v151, 1.0 op_sel:[1,1,0]
	v_pk_fma_f32 v[118:119], v[130:131], v[134:135], v[118:119] op_sel_hi:[0,1,1]
	v_pk_fma_f32 v[116:117], v[130:131], v[136:137], v[116:117] op_sel_hi:[0,1,1]
	v_pk_fma_f32 v[114:115], v[130:131], v[138:139], v[114:115] op_sel_hi:[0,1,1]
	v_pk_fma_f32 v[112:113], v[130:131], v[140:141], v[112:113] op_sel_hi:[0,1,1]
	v_cvt_scalef32_pk_f32_fp4 v[134:135], v152, 1.0
	v_cvt_scalef32_pk_f32_fp4 v[136:137], v152, 1.0 op_sel:[1,0,0]
	v_cvt_scalef32_pk_f32_fp4 v[138:139], v152, 1.0 op_sel:[0,1,0]
	v_cvt_scalef32_pk_f32_fp4 v[140:141], v152, 1.0 op_sel:[1,1,0]
	v_pk_fma_f32 v[80:81], v[130:131], v[134:135], v[80:81] op_sel_hi:[0,1,1]
	v_pk_fma_f32 v[78:79], v[130:131], v[136:137], v[78:79] op_sel_hi:[0,1,1]
	v_pk_fma_f32 v[76:77], v[130:131], v[138:139], v[76:77] op_sel_hi:[0,1,1]
	v_pk_fma_f32 v[74:75], v[130:131], v[140:141], v[74:75] op_sel_hi:[0,1,1]
	v_cvt_scalef32_pk_f32_fp4 v[134:135], v153, 1.0
	v_cvt_scalef32_pk_f32_fp4 v[136:137], v153, 1.0 op_sel:[1,0,0]
	v_cvt_scalef32_pk_f32_fp4 v[138:139], v153, 1.0 op_sel:[0,1,0]
	v_cvt_scalef32_pk_f32_fp4 v[140:141], v153, 1.0 op_sel:[1,1,0]
	v_pk_fma_f32 v[72:73], v[130:131], v[134:135], v[72:73] op_sel_hi:[0,1,1]
	v_pk_fma_f32 v[70:71], v[130:131], v[136:137], v[70:71] op_sel_hi:[0,1,1]
	v_pk_fma_f32 v[68:69], v[130:131], v[138:139], v[68:69] op_sel_hi:[0,1,1]
	v_pk_fma_f32 v[66:67], v[130:131], v[140:141], v[66:67] op_sel_hi:[0,1,1]
	s_waitcnt vmcnt(14)
	v_cvt_scalef32_pk_f32_fp4 v[134:135], v232, 1.0
	v_cvt_scalef32_pk_f32_fp4 v[136:137], v232, 1.0 op_sel:[1,0,0]
	v_cvt_scalef32_pk_f32_fp4 v[138:139], v232, 1.0 op_sel:[0,1,0]
	v_cvt_scalef32_pk_f32_fp4 v[140:141], v232, 1.0 op_sel:[1,1,0]
	v_pk_fma_f32 v[34:35], v[130:131], v[134:135], v[34:35] op_sel_hi:[0,1,1]
	v_pk_fma_f32 v[36:37], v[130:131], v[136:137], v[36:37] op_sel_hi:[0,1,1]
	v_pk_fma_f32 v[38:39], v[130:131], v[138:139], v[38:39] op_sel_hi:[0,1,1]
	v_pk_fma_f32 v[40:41], v[130:131], v[140:141], v[40:41] op_sel_hi:[0,1,1]
	v_cvt_scalef32_pk_f32_fp4 v[134:135], v233, 1.0
	v_cvt_scalef32_pk_f32_fp4 v[136:137], v233, 1.0 op_sel:[1,0,0]
	v_cvt_scalef32_pk_f32_fp4 v[138:139], v233, 1.0 op_sel:[0,1,0]
	v_cvt_scalef32_pk_f32_fp4 v[140:141], v233, 1.0 op_sel:[1,1,0]
	v_pk_fma_f32 v[42:43], v[130:131], v[134:135], v[42:43] op_sel_hi:[0,1,1]
	v_pk_fma_f32 v[44:45], v[130:131], v[136:137], v[44:45] op_sel_hi:[0,1,1]
	v_pk_fma_f32 v[46:47], v[130:131], v[138:139], v[46:47] op_sel_hi:[0,1,1]
	v_pk_fma_f32 v[48:49], v[130:131], v[140:141], v[48:49] op_sel_hi:[0,1,1]
	v_cvt_scalef32_pk_f32_fp4 v[134:135], v234, 1.0
	v_cvt_scalef32_pk_f32_fp4 v[136:137], v234, 1.0 op_sel:[1,0,0]
	v_cvt_scalef32_pk_f32_fp4 v[138:139], v234, 1.0 op_sel:[0,1,0]
	v_cvt_scalef32_pk_f32_fp4 v[140:141], v234, 1.0 op_sel:[1,1,0]
	v_pk_fma_f32 v[50:51], v[130:131], v[134:135], v[50:51] op_sel_hi:[0,1,1]
	v_pk_fma_f32 v[52:53], v[130:131], v[136:137], v[52:53] op_sel_hi:[0,1,1]
	v_pk_fma_f32 v[54:55], v[130:131], v[138:139], v[54:55] op_sel_hi:[0,1,1]
	v_pk_fma_f32 v[56:57], v[130:131], v[140:141], v[56:57] op_sel_hi:[0,1,1]
	v_cvt_scalef32_pk_f32_fp4 v[134:135], v235, 1.0
	v_cvt_scalef32_pk_f32_fp4 v[136:137], v235, 1.0 op_sel:[1,0,0]
	v_cvt_scalef32_pk_f32_fp4 v[138:139], v235, 1.0 op_sel:[0,1,0]
	v_cvt_scalef32_pk_f32_fp4 v[140:141], v235, 1.0 op_sel:[1,1,0]
	v_pk_fma_f32 v[58:59], v[130:131], v[134:135], v[58:59] op_sel_hi:[0,1,1]
	v_pk_fma_f32 v[60:61], v[130:131], v[136:137], v[60:61] op_sel_hi:[0,1,1]
	v_pk_fma_f32 v[62:63], v[130:131], v[138:139], v[62:63] op_sel_hi:[0,1,1]
	v_pk_fma_f32 v[64:65], v[130:131], v[140:141], v[64:65] op_sel_hi:[0,1,1]
	v_mad_u64_u32 v[248:249], vcc, v250, s0, v[86:87]
	global_load_dwordx4 v[150:153], v[248:249], off
	global_load_dwordx4 v[232:235], v[248:249], off offset:256
	ds_read_b32 v227, v131 offset:96
	ds_read_b32 v130, v132 offset:96
	s_waitcnt vmcnt(15)
	v_cvt_scalef32_pk_f32_fp4 v[134:135], v236, 1.0
	v_cvt_scalef32_pk_f32_fp4 v[136:137], v236, 1.0 op_sel:[1,0,0]
	v_cvt_scalef32_pk_f32_fp4 v[138:139], v236, 1.0 op_sel:[0,1,0]
	v_cvt_scalef32_pk_f32_fp4 v[140:141], v236, 1.0 op_sel:[1,1,0]
	s_waitcnt lgkmcnt(0)
	v_pk_fma_f32 v[128:129], v[130:131], v[134:135], v[128:129] op_sel_hi:[0,1,1]
	v_pk_fma_f32 v[126:127], v[130:131], v[136:137], v[126:127] op_sel_hi:[0,1,1]
	v_pk_fma_f32 v[122:123], v[130:131], v[138:139], v[122:123] op_sel_hi:[0,1,1]
	v_pk_fma_f32 v[120:121], v[130:131], v[140:141], v[120:121] op_sel_hi:[0,1,1]
	v_cvt_scalef32_pk_f32_fp4 v[134:135], v237, 1.0
	v_cvt_scalef32_pk_f32_fp4 v[136:137], v237, 1.0 op_sel:[1,0,0]
	v_cvt_scalef32_pk_f32_fp4 v[138:139], v237, 1.0 op_sel:[0,1,0]
	v_cvt_scalef32_pk_f32_fp4 v[140:141], v237, 1.0 op_sel:[1,1,0]
	v_pk_fma_f32 v[118:119], v[130:131], v[134:135], v[118:119] op_sel_hi:[0,1,1]
	v_pk_fma_f32 v[116:117], v[130:131], v[136:137], v[116:117] op_sel_hi:[0,1,1]
	v_pk_fma_f32 v[114:115], v[130:131], v[138:139], v[114:115] op_sel_hi:[0,1,1]
	v_pk_fma_f32 v[112:113], v[130:131], v[140:141], v[112:113] op_sel_hi:[0,1,1]
	v_cvt_scalef32_pk_f32_fp4 v[134:135], v238, 1.0
	v_cvt_scalef32_pk_f32_fp4 v[136:137], v238, 1.0 op_sel:[1,0,0]
	v_cvt_scalef32_pk_f32_fp4 v[138:139], v238, 1.0 op_sel:[0,1,0]
	v_cvt_scalef32_pk_f32_fp4 v[140:141], v238, 1.0 op_sel:[1,1,0]
	v_pk_fma_f32 v[80:81], v[130:131], v[134:135], v[80:81] op_sel_hi:[0,1,1]
	v_pk_fma_f32 v[78:79], v[130:131], v[136:137], v[78:79] op_sel_hi:[0,1,1]
	v_pk_fma_f32 v[76:77], v[130:131], v[138:139], v[76:77] op_sel_hi:[0,1,1]
	v_pk_fma_f32 v[74:75], v[130:131], v[140:141], v[74:75] op_sel_hi:[0,1,1]
	v_cvt_scalef32_pk_f32_fp4 v[134:135], v239, 1.0
	v_cvt_scalef32_pk_f32_fp4 v[136:137], v239, 1.0 op_sel:[1,0,0]
	v_cvt_scalef32_pk_f32_fp4 v[138:139], v239, 1.0 op_sel:[0,1,0]
	v_cvt_scalef32_pk_f32_fp4 v[140:141], v239, 1.0 op_sel:[1,1,0]
	v_pk_fma_f32 v[72:73], v[130:131], v[134:135], v[72:73] op_sel_hi:[0,1,1]
	v_pk_fma_f32 v[70:71], v[130:131], v[136:137], v[70:71] op_sel_hi:[0,1,1]
	v_pk_fma_f32 v[68:69], v[130:131], v[138:139], v[68:69] op_sel_hi:[0,1,1]
	v_pk_fma_f32 v[66:67], v[130:131], v[140:141], v[66:67] op_sel_hi:[0,1,1]
	s_waitcnt vmcnt(14)
	v_cvt_scalef32_pk_f32_fp4 v[134:135], v240, 1.0
	v_cvt_scalef32_pk_f32_fp4 v[136:137], v240, 1.0 op_sel:[1,0,0]
	v_cvt_scalef32_pk_f32_fp4 v[138:139], v240, 1.0 op_sel:[0,1,0]
	v_cvt_scalef32_pk_f32_fp4 v[140:141], v240, 1.0 op_sel:[1,1,0]
	v_pk_fma_f32 v[34:35], v[130:131], v[134:135], v[34:35] op_sel_hi:[0,1,1]
	v_pk_fma_f32 v[36:37], v[130:131], v[136:137], v[36:37] op_sel_hi:[0,1,1]
	v_pk_fma_f32 v[38:39], v[130:131], v[138:139], v[38:39] op_sel_hi:[0,1,1]
	v_pk_fma_f32 v[40:41], v[130:131], v[140:141], v[40:41] op_sel_hi:[0,1,1]
	v_cvt_scalef32_pk_f32_fp4 v[134:135], v241, 1.0
	v_cvt_scalef32_pk_f32_fp4 v[136:137], v241, 1.0 op_sel:[1,0,0]
	v_cvt_scalef32_pk_f32_fp4 v[138:139], v241, 1.0 op_sel:[0,1,0]
	v_cvt_scalef32_pk_f32_fp4 v[140:141], v241, 1.0 op_sel:[1,1,0]
	v_pk_fma_f32 v[42:43], v[130:131], v[134:135], v[42:43] op_sel_hi:[0,1,1]
	v_pk_fma_f32 v[44:45], v[130:131], v[136:137], v[44:45] op_sel_hi:[0,1,1]
	v_pk_fma_f32 v[46:47], v[130:131], v[138:139], v[46:47] op_sel_hi:[0,1,1]
	v_pk_fma_f32 v[48:49], v[130:131], v[140:141], v[48:49] op_sel_hi:[0,1,1]
	v_cvt_scalef32_pk_f32_fp4 v[134:135], v242, 1.0
	v_cvt_scalef32_pk_f32_fp4 v[136:137], v242, 1.0 op_sel:[1,0,0]
	v_cvt_scalef32_pk_f32_fp4 v[138:139], v242, 1.0 op_sel:[0,1,0]
	v_cvt_scalef32_pk_f32_fp4 v[140:141], v242, 1.0 op_sel:[1,1,0]
	v_pk_fma_f32 v[50:51], v[130:131], v[134:135], v[50:51] op_sel_hi:[0,1,1]
	v_pk_fma_f32 v[52:53], v[130:131], v[136:137], v[52:53] op_sel_hi:[0,1,1]
	v_pk_fma_f32 v[54:55], v[130:131], v[138:139], v[54:55] op_sel_hi:[0,1,1]
	v_pk_fma_f32 v[56:57], v[130:131], v[140:141], v[56:57] op_sel_hi:[0,1,1]
	v_cvt_scalef32_pk_f32_fp4 v[134:135], v243, 1.0
	v_cvt_scalef32_pk_f32_fp4 v[136:137], v243, 1.0 op_sel:[1,0,0]
	v_cvt_scalef32_pk_f32_fp4 v[138:139], v243, 1.0 op_sel:[0,1,0]
	v_cvt_scalef32_pk_f32_fp4 v[140:141], v243, 1.0 op_sel:[1,1,0]
	v_pk_fma_f32 v[58:59], v[130:131], v[134:135], v[58:59] op_sel_hi:[0,1,1]
	v_pk_fma_f32 v[60:61], v[130:131], v[136:137], v[60:61] op_sel_hi:[0,1,1]
	v_pk_fma_f32 v[62:63], v[130:131], v[138:139], v[62:63] op_sel_hi:[0,1,1]
	v_pk_fma_f32 v[64:65], v[130:131], v[140:141], v[64:65] op_sel_hi:[0,1,1]
	v_mad_u64_u32 v[248:249], vcc, v227, s0, v[86:87]
	global_load_dwordx4 v[236:239], v[248:249], off
	global_load_dwordx4 v[240:243], v[248:249], off offset:256
	ds_read_b32 v250, v131 offset:112
	ds_read_b32 v130, v132 offset:112
	s_waitcnt vmcnt(15)
	v_cvt_scalef32_pk_f32_fp4 v[134:135], v244, 1.0
	v_cvt_scalef32_pk_f32_fp4 v[136:137], v244, 1.0 op_sel:[1,0,0]
	v_cvt_scalef32_pk_f32_fp4 v[138:139], v244, 1.0 op_sel:[0,1,0]
	v_cvt_scalef32_pk_f32_fp4 v[140:141], v244, 1.0 op_sel:[1,1,0]
	s_waitcnt lgkmcnt(0)
	v_pk_fma_f32 v[128:129], v[130:131], v[134:135], v[128:129] op_sel_hi:[0,1,1]
	v_pk_fma_f32 v[126:127], v[130:131], v[136:137], v[126:127] op_sel_hi:[0,1,1]
	v_pk_fma_f32 v[122:123], v[130:131], v[138:139], v[122:123] op_sel_hi:[0,1,1]
	v_pk_fma_f32 v[120:121], v[130:131], v[140:141], v[120:121] op_sel_hi:[0,1,1]
	v_cvt_scalef32_pk_f32_fp4 v[134:135], v245, 1.0
	v_cvt_scalef32_pk_f32_fp4 v[136:137], v245, 1.0 op_sel:[1,0,0]
	v_cvt_scalef32_pk_f32_fp4 v[138:139], v245, 1.0 op_sel:[0,1,0]
	v_cvt_scalef32_pk_f32_fp4 v[140:141], v245, 1.0 op_sel:[1,1,0]
	v_pk_fma_f32 v[118:119], v[130:131], v[134:135], v[118:119] op_sel_hi:[0,1,1]
	v_pk_fma_f32 v[116:117], v[130:131], v[136:137], v[116:117] op_sel_hi:[0,1,1]
	v_pk_fma_f32 v[114:115], v[130:131], v[138:139], v[114:115] op_sel_hi:[0,1,1]
	v_pk_fma_f32 v[112:113], v[130:131], v[140:141], v[112:113] op_sel_hi:[0,1,1]
	v_cvt_scalef32_pk_f32_fp4 v[134:135], v246, 1.0
	v_cvt_scalef32_pk_f32_fp4 v[136:137], v246, 1.0 op_sel:[1,0,0]
	v_cvt_scalef32_pk_f32_fp4 v[138:139], v246, 1.0 op_sel:[0,1,0]
	v_cvt_scalef32_pk_f32_fp4 v[140:141], v246, 1.0 op_sel:[1,1,0]
	v_pk_fma_f32 v[80:81], v[130:131], v[134:135], v[80:81] op_sel_hi:[0,1,1]
	v_pk_fma_f32 v[78:79], v[130:131], v[136:137], v[78:79] op_sel_hi:[0,1,1]
	v_pk_fma_f32 v[76:77], v[130:131], v[138:139], v[76:77] op_sel_hi:[0,1,1]
	v_pk_fma_f32 v[74:75], v[130:131], v[140:141], v[74:75] op_sel_hi:[0,1,1]
	v_cvt_scalef32_pk_f32_fp4 v[134:135], v247, 1.0
	v_cvt_scalef32_pk_f32_fp4 v[136:137], v247, 1.0 op_sel:[1,0,0]
	v_cvt_scalef32_pk_f32_fp4 v[138:139], v247, 1.0 op_sel:[0,1,0]
	v_cvt_scalef32_pk_f32_fp4 v[140:141], v247, 1.0 op_sel:[1,1,0]
	v_pk_fma_f32 v[72:73], v[130:131], v[134:135], v[72:73] op_sel_hi:[0,1,1]
	v_pk_fma_f32 v[70:71], v[130:131], v[136:137], v[70:71] op_sel_hi:[0,1,1]
	v_pk_fma_f32 v[68:69], v[130:131], v[138:139], v[68:69] op_sel_hi:[0,1,1]
	v_pk_fma_f32 v[66:67], v[130:131], v[140:141], v[66:67] op_sel_hi:[0,1,1]
	s_waitcnt vmcnt(14)
	v_cvt_scalef32_pk_f32_fp4 v[134:135], v228, 1.0
	v_cvt_scalef32_pk_f32_fp4 v[136:137], v228, 1.0 op_sel:[1,0,0]
	v_cvt_scalef32_pk_f32_fp4 v[138:139], v228, 1.0 op_sel:[0,1,0]
	v_cvt_scalef32_pk_f32_fp4 v[140:141], v228, 1.0 op_sel:[1,1,0]
	v_pk_fma_f32 v[34:35], v[130:131], v[134:135], v[34:35] op_sel_hi:[0,1,1]
	v_pk_fma_f32 v[36:37], v[130:131], v[136:137], v[36:37] op_sel_hi:[0,1,1]
	v_pk_fma_f32 v[38:39], v[130:131], v[138:139], v[38:39] op_sel_hi:[0,1,1]
	v_pk_fma_f32 v[40:41], v[130:131], v[140:141], v[40:41] op_sel_hi:[0,1,1]
	v_cvt_scalef32_pk_f32_fp4 v[134:135], v229, 1.0
	v_cvt_scalef32_pk_f32_fp4 v[136:137], v229, 1.0 op_sel:[1,0,0]
	v_cvt_scalef32_pk_f32_fp4 v[138:139], v229, 1.0 op_sel:[0,1,0]
	v_cvt_scalef32_pk_f32_fp4 v[140:141], v229, 1.0 op_sel:[1,1,0]
	v_pk_fma_f32 v[42:43], v[130:131], v[134:135], v[42:43] op_sel_hi:[0,1,1]
	v_pk_fma_f32 v[44:45], v[130:131], v[136:137], v[44:45] op_sel_hi:[0,1,1]
	v_pk_fma_f32 v[46:47], v[130:131], v[138:139], v[46:47] op_sel_hi:[0,1,1]
	v_pk_fma_f32 v[48:49], v[130:131], v[140:141], v[48:49] op_sel_hi:[0,1,1]
	v_cvt_scalef32_pk_f32_fp4 v[134:135], v230, 1.0
	v_cvt_scalef32_pk_f32_fp4 v[136:137], v230, 1.0 op_sel:[1,0,0]
	v_cvt_scalef32_pk_f32_fp4 v[138:139], v230, 1.0 op_sel:[0,1,0]
	v_cvt_scalef32_pk_f32_fp4 v[140:141], v230, 1.0 op_sel:[1,1,0]
	v_pk_fma_f32 v[50:51], v[130:131], v[134:135], v[50:51] op_sel_hi:[0,1,1]
	v_pk_fma_f32 v[52:53], v[130:131], v[136:137], v[52:53] op_sel_hi:[0,1,1]
	v_pk_fma_f32 v[54:55], v[130:131], v[138:139], v[54:55] op_sel_hi:[0,1,1]
	v_pk_fma_f32 v[56:57], v[130:131], v[140:141], v[56:57] op_sel_hi:[0,1,1]
	v_cvt_scalef32_pk_f32_fp4 v[134:135], v231, 1.0
	v_cvt_scalef32_pk_f32_fp4 v[136:137], v231, 1.0 op_sel:[1,0,0]
	v_cvt_scalef32_pk_f32_fp4 v[138:139], v231, 1.0 op_sel:[0,1,0]
	v_cvt_scalef32_pk_f32_fp4 v[140:141], v231, 1.0 op_sel:[1,1,0]
	v_pk_fma_f32 v[58:59], v[130:131], v[134:135], v[58:59] op_sel_hi:[0,1,1]
	v_pk_fma_f32 v[60:61], v[130:131], v[136:137], v[60:61] op_sel_hi:[0,1,1]
	v_pk_fma_f32 v[62:63], v[130:131], v[138:139], v[62:63] op_sel_hi:[0,1,1]
	v_pk_fma_f32 v[64:65], v[130:131], v[140:141], v[64:65] op_sel_hi:[0,1,1]
	v_mad_u64_u32 v[248:249], vcc, v250, s0, v[86:87]
	global_load_dwordx4 v[244:247], v[248:249], off
	global_load_dwordx4 v[228:231], v[248:249], off offset:256
	ds_read_b32 v227, v131 offset:128
	ds_read_b32 v130, v132 offset:128
	s_waitcnt vmcnt(15)
	v_cvt_scalef32_pk_f32_fp4 v[134:135], v10, 1.0
	v_cvt_scalef32_pk_f32_fp4 v[136:137], v10, 1.0 op_sel:[1,0,0]
	v_cvt_scalef32_pk_f32_fp4 v[138:139], v10, 1.0 op_sel:[0,1,0]
	v_cvt_scalef32_pk_f32_fp4 v[140:141], v10, 1.0 op_sel:[1,1,0]
	s_waitcnt lgkmcnt(0)
	v_pk_fma_f32 v[128:129], v[130:131], v[134:135], v[128:129] op_sel_hi:[0,1,1]
	v_pk_fma_f32 v[126:127], v[130:131], v[136:137], v[126:127] op_sel_hi:[0,1,1]
	v_pk_fma_f32 v[122:123], v[130:131], v[138:139], v[122:123] op_sel_hi:[0,1,1]
	v_pk_fma_f32 v[120:121], v[130:131], v[140:141], v[120:121] op_sel_hi:[0,1,1]
	v_cvt_scalef32_pk_f32_fp4 v[134:135], v11, 1.0
	v_cvt_scalef32_pk_f32_fp4 v[136:137], v11, 1.0 op_sel:[1,0,0]
	v_cvt_scalef32_pk_f32_fp4 v[138:139], v11, 1.0 op_sel:[0,1,0]
	v_cvt_scalef32_pk_f32_fp4 v[140:141], v11, 1.0 op_sel:[1,1,0]
	v_pk_fma_f32 v[118:119], v[130:131], v[134:135], v[118:119] op_sel_hi:[0,1,1]
	v_pk_fma_f32 v[116:117], v[130:131], v[136:137], v[116:117] op_sel_hi:[0,1,1]
	v_pk_fma_f32 v[114:115], v[130:131], v[138:139], v[114:115] op_sel_hi:[0,1,1]
	v_pk_fma_f32 v[112:113], v[130:131], v[140:141], v[112:113] op_sel_hi:[0,1,1]
	v_cvt_scalef32_pk_f32_fp4 v[134:135], v12, 1.0
	v_cvt_scalef32_pk_f32_fp4 v[136:137], v12, 1.0 op_sel:[1,0,0]
	v_cvt_scalef32_pk_f32_fp4 v[138:139], v12, 1.0 op_sel:[0,1,0]
	v_cvt_scalef32_pk_f32_fp4 v[140:141], v12, 1.0 op_sel:[1,1,0]
	v_pk_fma_f32 v[80:81], v[130:131], v[134:135], v[80:81] op_sel_hi:[0,1,1]
	v_pk_fma_f32 v[78:79], v[130:131], v[136:137], v[78:79] op_sel_hi:[0,1,1]
	v_pk_fma_f32 v[76:77], v[130:131], v[138:139], v[76:77] op_sel_hi:[0,1,1]
	v_pk_fma_f32 v[74:75], v[130:131], v[140:141], v[74:75] op_sel_hi:[0,1,1]
	v_cvt_scalef32_pk_f32_fp4 v[134:135], v13, 1.0
	v_cvt_scalef32_pk_f32_fp4 v[136:137], v13, 1.0 op_sel:[1,0,0]
	v_cvt_scalef32_pk_f32_fp4 v[138:139], v13, 1.0 op_sel:[0,1,0]
	v_cvt_scalef32_pk_f32_fp4 v[140:141], v13, 1.0 op_sel:[1,1,0]
	v_pk_fma_f32 v[72:73], v[130:131], v[134:135], v[72:73] op_sel_hi:[0,1,1]
	v_pk_fma_f32 v[70:71], v[130:131], v[136:137], v[70:71] op_sel_hi:[0,1,1]
	v_pk_fma_f32 v[68:69], v[130:131], v[138:139], v[68:69] op_sel_hi:[0,1,1]
	v_pk_fma_f32 v[66:67], v[130:131], v[140:141], v[66:67] op_sel_hi:[0,1,1]
	s_waitcnt vmcnt(14)
	v_cvt_scalef32_pk_f32_fp4 v[134:135], v2, 1.0
	v_cvt_scalef32_pk_f32_fp4 v[136:137], v2, 1.0 op_sel:[1,0,0]
	v_cvt_scalef32_pk_f32_fp4 v[138:139], v2, 1.0 op_sel:[0,1,0]
	v_cvt_scalef32_pk_f32_fp4 v[140:141], v2, 1.0 op_sel:[1,1,0]
	v_pk_fma_f32 v[34:35], v[130:131], v[134:135], v[34:35] op_sel_hi:[0,1,1]
	v_pk_fma_f32 v[36:37], v[130:131], v[136:137], v[36:37] op_sel_hi:[0,1,1]
	v_pk_fma_f32 v[38:39], v[130:131], v[138:139], v[38:39] op_sel_hi:[0,1,1]
	v_pk_fma_f32 v[40:41], v[130:131], v[140:141], v[40:41] op_sel_hi:[0,1,1]
	v_cvt_scalef32_pk_f32_fp4 v[134:135], v3, 1.0
	v_cvt_scalef32_pk_f32_fp4 v[136:137], v3, 1.0 op_sel:[1,0,0]
	v_cvt_scalef32_pk_f32_fp4 v[138:139], v3, 1.0 op_sel:[0,1,0]
	v_cvt_scalef32_pk_f32_fp4 v[140:141], v3, 1.0 op_sel:[1,1,0]
	v_pk_fma_f32 v[42:43], v[130:131], v[134:135], v[42:43] op_sel_hi:[0,1,1]
	v_pk_fma_f32 v[44:45], v[130:131], v[136:137], v[44:45] op_sel_hi:[0,1,1]
	v_pk_fma_f32 v[46:47], v[130:131], v[138:139], v[46:47] op_sel_hi:[0,1,1]
	v_pk_fma_f32 v[48:49], v[130:131], v[140:141], v[48:49] op_sel_hi:[0,1,1]
	v_cvt_scalef32_pk_f32_fp4 v[134:135], v4, 1.0
	v_cvt_scalef32_pk_f32_fp4 v[136:137], v4, 1.0 op_sel:[1,0,0]
	v_cvt_scalef32_pk_f32_fp4 v[138:139], v4, 1.0 op_sel:[0,1,0]
	v_cvt_scalef32_pk_f32_fp4 v[140:141], v4, 1.0 op_sel:[1,1,0]
	v_pk_fma_f32 v[50:51], v[130:131], v[134:135], v[50:51] op_sel_hi:[0,1,1]
	v_pk_fma_f32 v[52:53], v[130:131], v[136:137], v[52:53] op_sel_hi:[0,1,1]
	v_pk_fma_f32 v[54:55], v[130:131], v[138:139], v[54:55] op_sel_hi:[0,1,1]
	v_pk_fma_f32 v[56:57], v[130:131], v[140:141], v[56:57] op_sel_hi:[0,1,1]
	v_cvt_scalef32_pk_f32_fp4 v[134:135], v5, 1.0
	v_cvt_scalef32_pk_f32_fp4 v[136:137], v5, 1.0 op_sel:[1,0,0]
	v_cvt_scalef32_pk_f32_fp4 v[138:139], v5, 1.0 op_sel:[0,1,0]
	v_cvt_scalef32_pk_f32_fp4 v[140:141], v5, 1.0 op_sel:[1,1,0]
	v_pk_fma_f32 v[58:59], v[130:131], v[134:135], v[58:59] op_sel_hi:[0,1,1]
	v_pk_fma_f32 v[60:61], v[130:131], v[136:137], v[60:61] op_sel_hi:[0,1,1]
	v_pk_fma_f32 v[62:63], v[130:131], v[138:139], v[62:63] op_sel_hi:[0,1,1]
	v_pk_fma_f32 v[64:65], v[130:131], v[140:141], v[64:65] op_sel_hi:[0,1,1]
	s_add_i32 s2, s2, 8
	v_add_u32_e32 v131, 0x80, v131
	v_add_u32_e32 v132, 0x80, v132
	s_cmp_lt_u32 s2, 24
	s_cbranch_scc1 .Lpv_loop
	ds_read_b32 v130, v132 offset:16
	s_waitcnt vmcnt(13)
	v_cvt_scalef32_pk_f32_fp4 v[134:135], v14, 1.0
	v_cvt_scalef32_pk_f32_fp4 v[136:137], v14, 1.0 op_sel:[1,0,0]
	v_cvt_scalef32_pk_f32_fp4 v[138:139], v14, 1.0 op_sel:[0,1,0]
	v_cvt_scalef32_pk_f32_fp4 v[140:141], v14, 1.0 op_sel:[1,1,0]
	s_waitcnt lgkmcnt(0)
	v_pk_fma_f32 v[128:129], v[130:131], v[134:135], v[128:129] op_sel_hi:[0,1,1]
	v_pk_fma_f32 v[126:127], v[130:131], v[136:137], v[126:127] op_sel_hi:[0,1,1]
	v_pk_fma_f32 v[122:123], v[130:131], v[138:139], v[122:123] op_sel_hi:[0,1,1]
	v_pk_fma_f32 v[120:121], v[130:131], v[140:141], v[120:121] op_sel_hi:[0,1,1]
	v_cvt_scalef32_pk_f32_fp4 v[134:135], v15, 1.0
	v_cvt_scalef32_pk_f32_fp4 v[136:137], v15, 1.0 op_sel:[1,0,0]
	v_cvt_scalef32_pk_f32_fp4 v[138:139], v15, 1.0 op_sel:[0,1,0]
	v_cvt_scalef32_pk_f32_fp4 v[140:141], v15, 1.0 op_sel:[1,1,0]
	v_pk_fma_f32 v[118:119], v[130:131], v[134:135], v[118:119] op_sel_hi:[0,1,1]
	v_pk_fma_f32 v[116:117], v[130:131], v[136:137], v[116:117] op_sel_hi:[0,1,1]
	v_pk_fma_f32 v[114:115], v[130:131], v[138:139], v[114:115] op_sel_hi:[0,1,1]
	v_pk_fma_f32 v[112:113], v[130:131], v[140:141], v[112:113] op_sel_hi:[0,1,1]
	v_cvt_scalef32_pk_f32_fp4 v[134:135], v16, 1.0
	v_cvt_scalef32_pk_f32_fp4 v[136:137], v16, 1.0 op_sel:[1,0,0]
	v_cvt_scalef32_pk_f32_fp4 v[138:139], v16, 1.0 op_sel:[0,1,0]
	v_cvt_scalef32_pk_f32_fp4 v[140:141], v16, 1.0 op_sel:[1,1,0]
	v_pk_fma_f32 v[80:81], v[130:131], v[134:135], v[80:81] op_sel_hi:[0,1,1]
	v_pk_fma_f32 v[78:79], v[130:131], v[136:137], v[78:79] op_sel_hi:[0,1,1]
	v_pk_fma_f32 v[76:77], v[130:131], v[138:139], v[76:77] op_sel_hi:[0,1,1]
	v_pk_fma_f32 v[74:75], v[130:131], v[140:141], v[74:75] op_sel_hi:[0,1,1]
	v_cvt_scalef32_pk_f32_fp4 v[134:135], v17, 1.0
	v_cvt_scalef32_pk_f32_fp4 v[136:137], v17, 1.0 op_sel:[1,0,0]
	v_cvt_scalef32_pk_f32_fp4 v[138:139], v17, 1.0 op_sel:[0,1,0]
	v_cvt_scalef32_pk_f32_fp4 v[140:141], v17, 1.0 op_sel:[1,1,0]
	v_pk_fma_f32 v[72:73], v[130:131], v[134:135], v[72:73] op_sel_hi:[0,1,1]
	v_pk_fma_f32 v[70:71], v[130:131], v[136:137], v[70:71] op_sel_hi:[0,1,1]
	v_pk_fma_f32 v[68:69], v[130:131], v[138:139], v[68:69] op_sel_hi:[0,1,1]
	v_pk_fma_f32 v[66:67], v[130:131], v[140:141], v[66:67] op_sel_hi:[0,1,1]
	s_waitcnt vmcnt(12)
	v_cvt_scalef32_pk_f32_fp4 v[134:135], v6, 1.0
	v_cvt_scalef32_pk_f32_fp4 v[136:137], v6, 1.0 op_sel:[1,0,0]
	v_cvt_scalef32_pk_f32_fp4 v[138:139], v6, 1.0 op_sel:[0,1,0]
	v_cvt_scalef32_pk_f32_fp4 v[140:141], v6, 1.0 op_sel:[1,1,0]
	v_pk_fma_f32 v[34:35], v[130:131], v[134:135], v[34:35] op_sel_hi:[0,1,1]
	v_pk_fma_f32 v[36:37], v[130:131], v[136:137], v[36:37] op_sel_hi:[0,1,1]
	v_pk_fma_f32 v[38:39], v[130:131], v[138:139], v[38:39] op_sel_hi:[0,1,1]
	v_pk_fma_f32 v[40:41], v[130:131], v[140:141], v[40:41] op_sel_hi:[0,1,1]
	v_cvt_scalef32_pk_f32_fp4 v[134:135], v7, 1.0
	v_cvt_scalef32_pk_f32_fp4 v[136:137], v7, 1.0 op_sel:[1,0,0]
	v_cvt_scalef32_pk_f32_fp4 v[138:139], v7, 1.0 op_sel:[0,1,0]
	v_cvt_scalef32_pk_f32_fp4 v[140:141], v7, 1.0 op_sel:[1,1,0]
	v_pk_fma_f32 v[42:43], v[130:131], v[134:135], v[42:43] op_sel_hi:[0,1,1]
	v_pk_fma_f32 v[44:45], v[130:131], v[136:137], v[44:45] op_sel_hi:[0,1,1]
	v_pk_fma_f32 v[46:47], v[130:131], v[138:139], v[46:47] op_sel_hi:[0,1,1]
	v_pk_fma_f32 v[48:49], v[130:131], v[140:141], v[48:49] op_sel_hi:[0,1,1]
	v_cvt_scalef32_pk_f32_fp4 v[134:135], v8, 1.0
	v_cvt_scalef32_pk_f32_fp4 v[136:137], v8, 1.0 op_sel:[1,0,0]
	v_cvt_scalef32_pk_f32_fp4 v[138:139], v8, 1.0 op_sel:[0,1,0]
	v_cvt_scalef32_pk_f32_fp4 v[140:141], v8, 1.0 op_sel:[1,1,0]
	v_pk_fma_f32 v[50:51], v[130:131], v[134:135], v[50:51] op_sel_hi:[0,1,1]
	v_pk_fma_f32 v[52:53], v[130:131], v[136:137], v[52:53] op_sel_hi:[0,1,1]
	v_pk_fma_f32 v[54:55], v[130:131], v[138:139], v[54:55] op_sel_hi:[0,1,1]
	v_pk_fma_f32 v[56:57], v[130:131], v[140:141], v[56:57] op_sel_hi:[0,1,1]
	v_cvt_scalef32_pk_f32_fp4 v[134:135], v9, 1.0
	v_cvt_scalef32_pk_f32_fp4 v[136:137], v9, 1.0 op_sel:[1,0,0]
	v_cvt_scalef32_pk_f32_fp4 v[138:139], v9, 1.0 op_sel:[0,1,0]
	v_cvt_scalef32_pk_f32_fp4 v[140:141], v9, 1.0 op_sel:[1,1,0]
	v_pk_fma_f32 v[58:59], v[130:131], v[134:135], v[58:59] op_sel_hi:[0,1,1]
	v_pk_fma_f32 v[60:61], v[130:131], v[136:137], v[60:61] op_sel_hi:[0,1,1]
	v_pk_fma_f32 v[62:63], v[130:131], v[138:139], v[62:63] op_sel_hi:[0,1,1]
	v_pk_fma_f32 v[64:65], v[130:131], v[140:141], v[64:65] op_sel_hi:[0,1,1]
	ds_read_b32 v130, v132 offset:32
	s_waitcnt vmcnt(11)
	v_cvt_scalef32_pk_f32_fp4 v[134:135], v22, 1.0
	v_cvt_scalef32_pk_f32_fp4 v[136:137], v22, 1.0 op_sel:[1,0,0]
	v_cvt_scalef32_pk_f32_fp4 v[138:139], v22, 1.0 op_sel:[0,1,0]
	v_cvt_scalef32_pk_f32_fp4 v[140:141], v22, 1.0 op_sel:[1,1,0]
	s_waitcnt lgkmcnt(0)
	v_pk_fma_f32 v[128:129], v[130:131], v[134:135], v[128:129] op_sel_hi:[0,1,1]
	v_pk_fma_f32 v[126:127], v[130:131], v[136:137], v[126:127] op_sel_hi:[0,1,1]
	v_pk_fma_f32 v[122:123], v[130:131], v[138:139], v[122:123] op_sel_hi:[0,1,1]
	v_pk_fma_f32 v[120:121], v[130:131], v[140:141], v[120:121] op_sel_hi:[0,1,1]
	v_cvt_scalef32_pk_f32_fp4 v[134:135], v23, 1.0
	v_cvt_scalef32_pk_f32_fp4 v[136:137], v23, 1.0 op_sel:[1,0,0]
	v_cvt_scalef32_pk_f32_fp4 v[138:139], v23, 1.0 op_sel:[0,1,0]
	v_cvt_scalef32_pk_f32_fp4 v[140:141], v23, 1.0 op_sel:[1,1,0]
	v_pk_fma_f32 v[118:119], v[130:131], v[134:135], v[118:119] op_sel_hi:[0,1,1]
	v_pk_fma_f32 v[116:117], v[130:131], v[136:137], v[116:117] op_sel_hi:[0,1,1]
	v_pk_fma_f32 v[114:115], v[130:131], v[138:139], v[114:115] op_sel_hi:[0,1,1]
	v_pk_fma_f32 v[112:113], v[130:131], v[140:141], v[112:113] op_sel_hi:[0,1,1]
	v_cvt_scalef32_pk_f32_fp4 v[134:135], v24, 1.0
	v_cvt_scalef32_pk_f32_fp4 v[136:137], v24, 1.0 op_sel:[1,0,0]
	v_cvt_scalef32_pk_f32_fp4 v[138:139], v24, 1.0 op_sel:[0,1,0]
	v_cvt_scalef32_pk_f32_fp4 v[140:141], v24, 1.0 op_sel:[1,1,0]
	v_pk_fma_f32 v[80:81], v[130:131], v[134:135], v[80:81] op_sel_hi:[0,1,1]
	v_pk_fma_f32 v[78:79], v[130:131], v[136:137], v[78:79] op_sel_hi:[0,1,1]
	v_pk_fma_f32 v[76:77], v[130:131], v[138:139], v[76:77] op_sel_hi:[0,1,1]
	v_pk_fma_f32 v[74:75], v[130:131], v[140:141], v[74:75] op_sel_hi:[0,1,1]
	v_cvt_scalef32_pk_f32_fp4 v[134:135], v25, 1.0
	v_cvt_scalef32_pk_f32_fp4 v[136:137], v25, 1.0 op_sel:[1,0,0]
	v_cvt_scalef32_pk_f32_fp4 v[138:139], v25, 1.0 op_sel:[0,1,0]
	v_cvt_scalef32_pk_f32_fp4 v[140:141], v25, 1.0 op_sel:[1,1,0]
	v_pk_fma_f32 v[72:73], v[130:131], v[134:135], v[72:73] op_sel_hi:[0,1,1]
	v_pk_fma_f32 v[70:71], v[130:131], v[136:137], v[70:71] op_sel_hi:[0,1,1]
	v_pk_fma_f32 v[68:69], v[130:131], v[138:139], v[68:69] op_sel_hi:[0,1,1]
	v_pk_fma_f32 v[66:67], v[130:131], v[140:141], v[66:67] op_sel_hi:[0,1,1]
	s_waitcnt vmcnt(10)
	v_cvt_scalef32_pk_f32_fp4 v[134:135], v18, 1.0
	v_cvt_scalef32_pk_f32_fp4 v[136:137], v18, 1.0 op_sel:[1,0,0]
	v_cvt_scalef32_pk_f32_fp4 v[138:139], v18, 1.0 op_sel:[0,1,0]
	v_cvt_scalef32_pk_f32_fp4 v[140:141], v18, 1.0 op_sel:[1,1,0]
	v_pk_fma_f32 v[34:35], v[130:131], v[134:135], v[34:35] op_sel_hi:[0,1,1]
	v_pk_fma_f32 v[36:37], v[130:131], v[136:137], v[36:37] op_sel_hi:[0,1,1]
	v_pk_fma_f32 v[38:39], v[130:131], v[138:139], v[38:39] op_sel_hi:[0,1,1]
	v_pk_fma_f32 v[40:41], v[130:131], v[140:141], v[40:41] op_sel_hi:[0,1,1]
	v_cvt_scalef32_pk_f32_fp4 v[134:135], v19, 1.0
	v_cvt_scalef32_pk_f32_fp4 v[136:137], v19, 1.0 op_sel:[1,0,0]
	v_cvt_scalef32_pk_f32_fp4 v[138:139], v19, 1.0 op_sel:[0,1,0]
	v_cvt_scalef32_pk_f32_fp4 v[140:141], v19, 1.0 op_sel:[1,1,0]
	v_pk_fma_f32 v[42:43], v[130:131], v[134:135], v[42:43] op_sel_hi:[0,1,1]
	v_pk_fma_f32 v[44:45], v[130:131], v[136:137], v[44:45] op_sel_hi:[0,1,1]
	v_pk_fma_f32 v[46:47], v[130:131], v[138:139], v[46:47] op_sel_hi:[0,1,1]
	v_pk_fma_f32 v[48:49], v[130:131], v[140:141], v[48:49] op_sel_hi:[0,1,1]
	v_cvt_scalef32_pk_f32_fp4 v[134:135], v20, 1.0
	v_cvt_scalef32_pk_f32_fp4 v[136:137], v20, 1.0 op_sel:[1,0,0]
	v_cvt_scalef32_pk_f32_fp4 v[138:139], v20, 1.0 op_sel:[0,1,0]
	v_cvt_scalef32_pk_f32_fp4 v[140:141], v20, 1.0 op_sel:[1,1,0]
	v_pk_fma_f32 v[50:51], v[130:131], v[134:135], v[50:51] op_sel_hi:[0,1,1]
	v_pk_fma_f32 v[52:53], v[130:131], v[136:137], v[52:53] op_sel_hi:[0,1,1]
	v_pk_fma_f32 v[54:55], v[130:131], v[138:139], v[54:55] op_sel_hi:[0,1,1]
	v_pk_fma_f32 v[56:57], v[130:131], v[140:141], v[56:57] op_sel_hi:[0,1,1]
	v_cvt_scalef32_pk_f32_fp4 v[134:135], v21, 1.0
	v_cvt_scalef32_pk_f32_fp4 v[136:137], v21, 1.0 op_sel:[1,0,0]
	v_cvt_scalef32_pk_f32_fp4 v[138:139], v21, 1.0 op_sel:[0,1,0]
	v_cvt_scalef32_pk_f32_fp4 v[140:141], v21, 1.0 op_sel:[1,1,0]
	v_pk_fma_f32 v[58:59], v[130:131], v[134:135], v[58:59] op_sel_hi:[0,1,1]
	v_pk_fma_f32 v[60:61], v[130:131], v[136:137], v[60:61] op_sel_hi:[0,1,1]
	v_pk_fma_f32 v[62:63], v[130:131], v[138:139], v[62:63] op_sel_hi:[0,1,1]
	v_pk_fma_f32 v[64:65], v[130:131], v[140:141], v[64:65] op_sel_hi:[0,1,1]
	ds_read_b32 v130, v132 offset:48
	s_waitcnt vmcnt(9)
	v_cvt_scalef32_pk_f32_fp4 v[134:135], v30, 1.0
	v_cvt_scalef32_pk_f32_fp4 v[136:137], v30, 1.0 op_sel:[1,0,0]
	v_cvt_scalef32_pk_f32_fp4 v[138:139], v30, 1.0 op_sel:[0,1,0]
	v_cvt_scalef32_pk_f32_fp4 v[140:141], v30, 1.0 op_sel:[1,1,0]
	s_waitcnt lgkmcnt(0)
	v_pk_fma_f32 v[128:129], v[130:131], v[134:135], v[128:129] op_sel_hi:[0,1,1]
	v_pk_fma_f32 v[126:127], v[130:131], v[136:137], v[126:127] op_sel_hi:[0,1,1]
	v_pk_fma_f32 v[122:123], v[130:131], v[138:139], v[122:123] op_sel_hi:[0,1,1]
	v_pk_fma_f32 v[120:121], v[130:131], v[140:141], v[120:121] op_sel_hi:[0,1,1]
	v_cvt_scalef32_pk_f32_fp4 v[134:135], v31, 1.0
	v_cvt_scalef32_pk_f32_fp4 v[136:137], v31, 1.0 op_sel:[1,0,0]
	v_cvt_scalef32_pk_f32_fp4 v[138:139], v31, 1.0 op_sel:[0,1,0]
	v_cvt_scalef32_pk_f32_fp4 v[140:141], v31, 1.0 op_sel:[1,1,0]
	v_pk_fma_f32 v[118:119], v[130:131], v[134:135], v[118:119] op_sel_hi:[0,1,1]
	v_pk_fma_f32 v[116:117], v[130:131], v[136:137], v[116:117] op_sel_hi:[0,1,1]
	v_pk_fma_f32 v[114:115], v[130:131], v[138:139], v[114:115] op_sel_hi:[0,1,1]
	v_pk_fma_f32 v[112:113], v[130:131], v[140:141], v[112:113] op_sel_hi:[0,1,1]
	v_cvt_scalef32_pk_f32_fp4 v[134:135], v32, 1.0
	v_cvt_scalef32_pk_f32_fp4 v[136:137], v32, 1.0 op_sel:[1,0,0]
	v_cvt_scalef32_pk_f32_fp4 v[138:139], v32, 1.0 op_sel:[0,1,0]
	v_cvt_scalef32_pk_f32_fp4 v[140:141], v32, 1.0 op_sel:[1,1,0]
	v_pk_fma_f32 v[80:81], v[130:131], v[134:135], v[80:81] op_sel_hi:[0,1,1]
	v_pk_fma_f32 v[78:79], v[130:131], v[136:137], v[78:79] op_sel_hi:[0,1,1]
	v_pk_fma_f32 v[76:77], v[130:131], v[138:139], v[76:77] op_sel_hi:[0,1,1]
	v_pk_fma_f32 v[74:75], v[130:131], v[140:141], v[74:75] op_sel_hi:[0,1,1]
	v_cvt_scalef32_pk_f32_fp4 v[134:135], v33, 1.0
	v_cvt_scalef32_pk_f32_fp4 v[136:137], v33, 1.0 op_sel:[1,0,0]
	v_cvt_scalef32_pk_f32_fp4 v[138:139], v33, 1.0 op_sel:[0,1,0]
	v_cvt_scalef32_pk_f32_fp4 v[140:141], v33, 1.0 op_sel:[1,1,0]
	v_pk_fma_f32 v[72:73], v[130:131], v[134:135], v[72:73] op_sel_hi:[0,1,1]
	v_pk_fma_f32 v[70:71], v[130:131], v[136:137], v[70:71] op_sel_hi:[0,1,1]
	v_pk_fma_f32 v[68:69], v[130:131], v[138:139], v[68:69] op_sel_hi:[0,1,1]
	v_pk_fma_f32 v[66:67], v[130:131], v[140:141], v[66:67] op_sel_hi:[0,1,1]
	s_waitcnt vmcnt(8)
	v_cvt_scalef32_pk_f32_fp4 v[134:135], v26, 1.0
	v_cvt_scalef32_pk_f32_fp4 v[136:137], v26, 1.0 op_sel:[1,0,0]
	v_cvt_scalef32_pk_f32_fp4 v[138:139], v26, 1.0 op_sel:[0,1,0]
	v_cvt_scalef32_pk_f32_fp4 v[140:141], v26, 1.0 op_sel:[1,1,0]
	v_pk_fma_f32 v[34:35], v[130:131], v[134:135], v[34:35] op_sel_hi:[0,1,1]
	v_pk_fma_f32 v[36:37], v[130:131], v[136:137], v[36:37] op_sel_hi:[0,1,1]
	v_pk_fma_f32 v[38:39], v[130:131], v[138:139], v[38:39] op_sel_hi:[0,1,1]
	v_pk_fma_f32 v[40:41], v[130:131], v[140:141], v[40:41] op_sel_hi:[0,1,1]
	v_cvt_scalef32_pk_f32_fp4 v[134:135], v27, 1.0
	v_cvt_scalef32_pk_f32_fp4 v[136:137], v27, 1.0 op_sel:[1,0,0]
	v_cvt_scalef32_pk_f32_fp4 v[138:139], v27, 1.0 op_sel:[0,1,0]
	v_cvt_scalef32_pk_f32_fp4 v[140:141], v27, 1.0 op_sel:[1,1,0]
	v_pk_fma_f32 v[42:43], v[130:131], v[134:135], v[42:43] op_sel_hi:[0,1,1]
	v_pk_fma_f32 v[44:45], v[130:131], v[136:137], v[44:45] op_sel_hi:[0,1,1]
	v_pk_fma_f32 v[46:47], v[130:131], v[138:139], v[46:47] op_sel_hi:[0,1,1]
	v_pk_fma_f32 v[48:49], v[130:131], v[140:141], v[48:49] op_sel_hi:[0,1,1]
	v_cvt_scalef32_pk_f32_fp4 v[134:135], v28, 1.0
	v_cvt_scalef32_pk_f32_fp4 v[136:137], v28, 1.0 op_sel:[1,0,0]
	v_cvt_scalef32_pk_f32_fp4 v[138:139], v28, 1.0 op_sel:[0,1,0]
	v_cvt_scalef32_pk_f32_fp4 v[140:141], v28, 1.0 op_sel:[1,1,0]
	v_pk_fma_f32 v[50:51], v[130:131], v[134:135], v[50:51] op_sel_hi:[0,1,1]
	v_pk_fma_f32 v[52:53], v[130:131], v[136:137], v[52:53] op_sel_hi:[0,1,1]
	v_pk_fma_f32 v[54:55], v[130:131], v[138:139], v[54:55] op_sel_hi:[0,1,1]
	v_pk_fma_f32 v[56:57], v[130:131], v[140:141], v[56:57] op_sel_hi:[0,1,1]
	v_cvt_scalef32_pk_f32_fp4 v[134:135], v29, 1.0
	v_cvt_scalef32_pk_f32_fp4 v[136:137], v29, 1.0 op_sel:[1,0,0]
	v_cvt_scalef32_pk_f32_fp4 v[138:139], v29, 1.0 op_sel:[0,1,0]
	v_cvt_scalef32_pk_f32_fp4 v[140:141], v29, 1.0 op_sel:[1,1,0]
	v_pk_fma_f32 v[58:59], v[130:131], v[134:135], v[58:59] op_sel_hi:[0,1,1]
	v_pk_fma_f32 v[60:61], v[130:131], v[136:137], v[60:61] op_sel_hi:[0,1,1]
	v_pk_fma_f32 v[62:63], v[130:131], v[138:139], v[62:63] op_sel_hi:[0,1,1]
	v_pk_fma_f32 v[64:65], v[130:131], v[140:141], v[64:65] op_sel_hi:[0,1,1]
	ds_read_b32 v130, v132 offset:64
	s_waitcnt vmcnt(7)
	v_cvt_scalef32_pk_f32_fp4 v[134:135], v142, 1.0
	v_cvt_scalef32_pk_f32_fp4 v[136:137], v142, 1.0 op_sel:[1,0,0]
	v_cvt_scalef32_pk_f32_fp4 v[138:139], v142, 1.0 op_sel:[0,1,0]
	v_cvt_scalef32_pk_f32_fp4 v[140:141], v142, 1.0 op_sel:[1,1,0]
	s_waitcnt lgkmcnt(0)
	v_pk_fma_f32 v[128:129], v[130:131], v[134:135], v[128:129] op_sel_hi:[0,1,1]
	v_pk_fma_f32 v[126:127], v[130:131], v[136:137], v[126:127] op_sel_hi:[0,1,1]
	v_pk_fma_f32 v[122:123], v[130:131], v[138:139], v[122:123] op_sel_hi:[0,1,1]
	v_pk_fma_f32 v[120:121], v[130:131], v[140:141], v[120:121] op_sel_hi:[0,1,1]
	v_cvt_scalef32_pk_f32_fp4 v[134:135], v143, 1.0
	v_cvt_scalef32_pk_f32_fp4 v[136:137], v143, 1.0 op_sel:[1,0,0]
	v_cvt_scalef32_pk_f32_fp4 v[138:139], v143, 1.0 op_sel:[0,1,0]
	v_cvt_scalef32_pk_f32_fp4 v[140:141], v143, 1.0 op_sel:[1,1,0]
	v_pk_fma_f32 v[118:119], v[130:131], v[134:135], v[118:119] op_sel_hi:[0,1,1]
	v_pk_fma_f32 v[116:117], v[130:131], v[136:137], v[116:117] op_sel_hi:[0,1,1]
	v_pk_fma_f32 v[114:115], v[130:131], v[138:139], v[114:115] op_sel_hi:[0,1,1]
	v_pk_fma_f32 v[112:113], v[130:131], v[140:141], v[112:113] op_sel_hi:[0,1,1]
	v_cvt_scalef32_pk_f32_fp4 v[134:135], v144, 1.0
	v_cvt_scalef32_pk_f32_fp4 v[136:137], v144, 1.0 op_sel:[1,0,0]
	v_cvt_scalef32_pk_f32_fp4 v[138:139], v144, 1.0 op_sel:[0,1,0]
	v_cvt_scalef32_pk_f32_fp4 v[140:141], v144, 1.0 op_sel:[1,1,0]
	v_pk_fma_f32 v[80:81], v[130:131], v[134:135], v[80:81] op_sel_hi:[0,1,1]
	v_pk_fma_f32 v[78:79], v[130:131], v[136:137], v[78:79] op_sel_hi:[0,1,1]
	v_pk_fma_f32 v[76:77], v[130:131], v[138:139], v[76:77] op_sel_hi:[0,1,1]
	v_pk_fma_f32 v[74:75], v[130:131], v[140:141], v[74:75] op_sel_hi:[0,1,1]
	v_cvt_scalef32_pk_f32_fp4 v[134:135], v145, 1.0
	v_cvt_scalef32_pk_f32_fp4 v[136:137], v145, 1.0 op_sel:[1,0,0]
	v_cvt_scalef32_pk_f32_fp4 v[138:139], v145, 1.0 op_sel:[0,1,0]
	v_cvt_scalef32_pk_f32_fp4 v[140:141], v145, 1.0 op_sel:[1,1,0]
	v_pk_fma_f32 v[72:73], v[130:131], v[134:135], v[72:73] op_sel_hi:[0,1,1]
	v_pk_fma_f32 v[70:71], v[130:131], v[136:137], v[70:71] op_sel_hi:[0,1,1]
	v_pk_fma_f32 v[68:69], v[130:131], v[138:139], v[68:69] op_sel_hi:[0,1,1]
	v_pk_fma_f32 v[66:67], v[130:131], v[140:141], v[66:67] op_sel_hi:[0,1,1]
	s_waitcnt vmcnt(6)
	v_cvt_scalef32_pk_f32_fp4 v[134:135], v146, 1.0
	v_cvt_scalef32_pk_f32_fp4 v[136:137], v146, 1.0 op_sel:[1,0,0]
	v_cvt_scalef32_pk_f32_fp4 v[138:139], v146, 1.0 op_sel:[0,1,0]
	v_cvt_scalef32_pk_f32_fp4 v[140:141], v146, 1.0 op_sel:[1,1,0]
	v_pk_fma_f32 v[34:35], v[130:131], v[134:135], v[34:35] op_sel_hi:[0,1,1]
	v_pk_fma_f32 v[36:37], v[130:131], v[136:137], v[36:37] op_sel_hi:[0,1,1]
	v_pk_fma_f32 v[38:39], v[130:131], v[138:139], v[38:39] op_sel_hi:[0,1,1]
	v_pk_fma_f32 v[40:41], v[130:131], v[140:141], v[40:41] op_sel_hi:[0,1,1]
	v_cvt_scalef32_pk_f32_fp4 v[134:135], v147, 1.0
	v_cvt_scalef32_pk_f32_fp4 v[136:137], v147, 1.0 op_sel:[1,0,0]
	v_cvt_scalef32_pk_f32_fp4 v[138:139], v147, 1.0 op_sel:[0,1,0]
	v_cvt_scalef32_pk_f32_fp4 v[140:141], v147, 1.0 op_sel:[1,1,0]
	v_pk_fma_f32 v[42:43], v[130:131], v[134:135], v[42:43] op_sel_hi:[0,1,1]
	v_pk_fma_f32 v[44:45], v[130:131], v[136:137], v[44:45] op_sel_hi:[0,1,1]
	v_pk_fma_f32 v[46:47], v[130:131], v[138:139], v[46:47] op_sel_hi:[0,1,1]
	v_pk_fma_f32 v[48:49], v[130:131], v[140:141], v[48:49] op_sel_hi:[0,1,1]
	v_cvt_scalef32_pk_f32_fp4 v[134:135], v148, 1.0
	v_cvt_scalef32_pk_f32_fp4 v[136:137], v148, 1.0 op_sel:[1,0,0]
	v_cvt_scalef32_pk_f32_fp4 v[138:139], v148, 1.0 op_sel:[0,1,0]
	v_cvt_scalef32_pk_f32_fp4 v[140:141], v148, 1.0 op_sel:[1,1,0]
	v_pk_fma_f32 v[50:51], v[130:131], v[134:135], v[50:51] op_sel_hi:[0,1,1]
	v_pk_fma_f32 v[52:53], v[130:131], v[136:137], v[52:53] op_sel_hi:[0,1,1]
	v_pk_fma_f32 v[54:55], v[130:131], v[138:139], v[54:55] op_sel_hi:[0,1,1]
	v_pk_fma_f32 v[56:57], v[130:131], v[140:141], v[56:57] op_sel_hi:[0,1,1]
	v_cvt_scalef32_pk_f32_fp4 v[134:135], v149, 1.0
	v_cvt_scalef32_pk_f32_fp4 v[136:137], v149, 1.0 op_sel:[1,0,0]
	v_cvt_scalef32_pk_f32_fp4 v[138:139], v149, 1.0 op_sel:[0,1,0]
	v_cvt_scalef32_pk_f32_fp4 v[140:141], v149, 1.0 op_sel:[1,1,0]
	v_pk_fma_f32 v[58:59], v[130:131], v[134:135], v[58:59] op_sel_hi:[0,1,1]
	v_pk_fma_f32 v[60:61], v[130:131], v[136:137], v[60:61] op_sel_hi:[0,1,1]
	v_pk_fma_f32 v[62:63], v[130:131], v[138:139], v[62:63] op_sel_hi:[0,1,1]
	v_pk_fma_f32 v[64:65], v[130:131], v[140:141], v[64:65] op_sel_hi:[0,1,1]
	ds_read_b32 v130, v132 offset:80
	s_waitcnt vmcnt(5)
	v_cvt_scalef32_pk_f32_fp4 v[134:135], v150, 1.0
	v_cvt_scalef32_pk_f32_fp4 v[136:137], v150, 1.0 op_sel:[1,0,0]
	v_cvt_scalef32_pk_f32_fp4 v[138:139], v150, 1.0 op_sel:[0,1,0]
	v_cvt_scalef32_pk_f32_fp4 v[140:141], v150, 1.0 op_sel:[1,1,0]
	s_waitcnt lgkmcnt(0)
	v_pk_fma_f32 v[128:129], v[130:131], v[134:135], v[128:129] op_sel_hi:[0,1,1]
	v_pk_fma_f32 v[126:127], v[130:131], v[136:137], v[126:127] op_sel_hi:[0,1,1]
	v_pk_fma_f32 v[122:123], v[130:131], v[138:139], v[122:123] op_sel_hi:[0,1,1]
	v_pk_fma_f32 v[120:121], v[130:131], v[140:141], v[120:121] op_sel_hi:[0,1,1]
	v_cvt_scalef32_pk_f32_fp4 v[134:135], v151, 1.0
	v_cvt_scalef32_pk_f32_fp4 v[136:137], v151, 1.0 op_sel:[1,0,0]
	v_cvt_scalef32_pk_f32_fp4 v[138:139], v151, 1.0 op_sel:[0,1,0]
	v_cvt_scalef32_pk_f32_fp4 v[140:141], v151, 1.0 op_sel:[1,1,0]
	v_pk_fma_f32 v[118:119], v[130:131], v[134:135], v[118:119] op_sel_hi:[0,1,1]
	v_pk_fma_f32 v[116:117], v[130:131], v[136:137], v[116:117] op_sel_hi:[0,1,1]
	v_pk_fma_f32 v[114:115], v[130:131], v[138:139], v[114:115] op_sel_hi:[0,1,1]
	v_pk_fma_f32 v[112:113], v[130:131], v[140:141], v[112:113] op_sel_hi:[0,1,1]
	v_cvt_scalef32_pk_f32_fp4 v[134:135], v152, 1.0
	v_cvt_scalef32_pk_f32_fp4 v[136:137], v152, 1.0 op_sel:[1,0,0]
	v_cvt_scalef32_pk_f32_fp4 v[138:139], v152, 1.0 op_sel:[0,1,0]
	v_cvt_scalef32_pk_f32_fp4 v[140:141], v152, 1.0 op_sel:[1,1,0]
	v_pk_fma_f32 v[80:81], v[130:131], v[134:135], v[80:81] op_sel_hi:[0,1,1]
	v_pk_fma_f32 v[78:79], v[130:131], v[136:137], v[78:79] op_sel_hi:[0,1,1]
	v_pk_fma_f32 v[76:77], v[130:131], v[138:139], v[76:77] op_sel_hi:[0,1,1]
	v_pk_fma_f32 v[74:75], v[130:131], v[140:141], v[74:75] op_sel_hi:[0,1,1]
	v_cvt_scalef32_pk_f32_fp4 v[134:135], v153, 1.0
	v_cvt_scalef32_pk_f32_fp4 v[136:137], v153, 1.0 op_sel:[1,0,0]
	v_cvt_scalef32_pk_f32_fp4 v[138:139], v153, 1.0 op_sel:[0,1,0]
	v_cvt_scalef32_pk_f32_fp4 v[140:141], v153, 1.0 op_sel:[1,1,0]
	v_pk_fma_f32 v[72:73], v[130:131], v[134:135], v[72:73] op_sel_hi:[0,1,1]
	v_pk_fma_f32 v[70:71], v[130:131], v[136:137], v[70:71] op_sel_hi:[0,1,1]
	v_pk_fma_f32 v[68:69], v[130:131], v[138:139], v[68:69] op_sel_hi:[0,1,1]
	v_pk_fma_f32 v[66:67], v[130:131], v[140:141], v[66:67] op_sel_hi:[0,1,1]
	s_waitcnt vmcnt(4)
	v_cvt_scalef32_pk_f32_fp4 v[134:135], v232, 1.0
	v_cvt_scalef32_pk_f32_fp4 v[136:137], v232, 1.0 op_sel:[1,0,0]
	v_cvt_scalef32_pk_f32_fp4 v[138:139], v232, 1.0 op_sel:[0,1,0]
	v_cvt_scalef32_pk_f32_fp4 v[140:141], v232, 1.0 op_sel:[1,1,0]
	v_pk_fma_f32 v[34:35], v[130:131], v[134:135], v[34:35] op_sel_hi:[0,1,1]
	v_pk_fma_f32 v[36:37], v[130:131], v[136:137], v[36:37] op_sel_hi:[0,1,1]
	v_pk_fma_f32 v[38:39], v[130:131], v[138:139], v[38:39] op_sel_hi:[0,1,1]
	v_pk_fma_f32 v[40:41], v[130:131], v[140:141], v[40:41] op_sel_hi:[0,1,1]
	v_cvt_scalef32_pk_f32_fp4 v[134:135], v233, 1.0
	v_cvt_scalef32_pk_f32_fp4 v[136:137], v233, 1.0 op_sel:[1,0,0]
	v_cvt_scalef32_pk_f32_fp4 v[138:139], v233, 1.0 op_sel:[0,1,0]
	v_cvt_scalef32_pk_f32_fp4 v[140:141], v233, 1.0 op_sel:[1,1,0]
	v_pk_fma_f32 v[42:43], v[130:131], v[134:135], v[42:43] op_sel_hi:[0,1,1]
	v_pk_fma_f32 v[44:45], v[130:131], v[136:137], v[44:45] op_sel_hi:[0,1,1]
	v_pk_fma_f32 v[46:47], v[130:131], v[138:139], v[46:47] op_sel_hi:[0,1,1]
	v_pk_fma_f32 v[48:49], v[130:131], v[140:141], v[48:49] op_sel_hi:[0,1,1]
	v_cvt_scalef32_pk_f32_fp4 v[134:135], v234, 1.0
	v_cvt_scalef32_pk_f32_fp4 v[136:137], v234, 1.0 op_sel:[1,0,0]
	v_cvt_scalef32_pk_f32_fp4 v[138:139], v234, 1.0 op_sel:[0,1,0]
	v_cvt_scalef32_pk_f32_fp4 v[140:141], v234, 1.0 op_sel:[1,1,0]
	v_pk_fma_f32 v[50:51], v[130:131], v[134:135], v[50:51] op_sel_hi:[0,1,1]
	v_pk_fma_f32 v[52:53], v[130:131], v[136:137], v[52:53] op_sel_hi:[0,1,1]
	v_pk_fma_f32 v[54:55], v[130:131], v[138:139], v[54:55] op_sel_hi:[0,1,1]
	v_pk_fma_f32 v[56:57], v[130:131], v[140:141], v[56:57] op_sel_hi:[0,1,1]
	v_cvt_scalef32_pk_f32_fp4 v[134:135], v235, 1.0
	v_cvt_scalef32_pk_f32_fp4 v[136:137], v235, 1.0 op_sel:[1,0,0]
	v_cvt_scalef32_pk_f32_fp4 v[138:139], v235, 1.0 op_sel:[0,1,0]
	v_cvt_scalef32_pk_f32_fp4 v[140:141], v235, 1.0 op_sel:[1,1,0]
	v_pk_fma_f32 v[58:59], v[130:131], v[134:135], v[58:59] op_sel_hi:[0,1,1]
	v_pk_fma_f32 v[60:61], v[130:131], v[136:137], v[60:61] op_sel_hi:[0,1,1]
	v_pk_fma_f32 v[62:63], v[130:131], v[138:139], v[62:63] op_sel_hi:[0,1,1]
	v_pk_fma_f32 v[64:65], v[130:131], v[140:141], v[64:65] op_sel_hi:[0,1,1]
	ds_read_b32 v130, v132 offset:96
	s_waitcnt vmcnt(3)
	v_cvt_scalef32_pk_f32_fp4 v[134:135], v236, 1.0
	v_cvt_scalef32_pk_f32_fp4 v[136:137], v236, 1.0 op_sel:[1,0,0]
	v_cvt_scalef32_pk_f32_fp4 v[138:139], v236, 1.0 op_sel:[0,1,0]
	v_cvt_scalef32_pk_f32_fp4 v[140:141], v236, 1.0 op_sel:[1,1,0]
	s_waitcnt lgkmcnt(0)
	v_pk_fma_f32 v[128:129], v[130:131], v[134:135], v[128:129] op_sel_hi:[0,1,1]
	v_pk_fma_f32 v[126:127], v[130:131], v[136:137], v[126:127] op_sel_hi:[0,1,1]
	v_pk_fma_f32 v[122:123], v[130:131], v[138:139], v[122:123] op_sel_hi:[0,1,1]
	v_pk_fma_f32 v[120:121], v[130:131], v[140:141], v[120:121] op_sel_hi:[0,1,1]
	v_cvt_scalef32_pk_f32_fp4 v[134:135], v237, 1.0
	v_cvt_scalef32_pk_f32_fp4 v[136:137], v237, 1.0 op_sel:[1,0,0]
	v_cvt_scalef32_pk_f32_fp4 v[138:139], v237, 1.0 op_sel:[0,1,0]
	v_cvt_scalef32_pk_f32_fp4 v[140:141], v237, 1.0 op_sel:[1,1,0]
	v_pk_fma_f32 v[118:119], v[130:131], v[134:135], v[118:119] op_sel_hi:[0,1,1]
	v_pk_fma_f32 v[116:117], v[130:131], v[136:137], v[116:117] op_sel_hi:[0,1,1]
	v_pk_fma_f32 v[114:115], v[130:131], v[138:139], v[114:115] op_sel_hi:[0,1,1]
	v_pk_fma_f32 v[112:113], v[130:131], v[140:141], v[112:113] op_sel_hi:[0,1,1]
	v_cvt_scalef32_pk_f32_fp4 v[134:135], v238, 1.0
	v_cvt_scalef32_pk_f32_fp4 v[136:137], v238, 1.0 op_sel:[1,0,0]
	v_cvt_scalef32_pk_f32_fp4 v[138:139], v238, 1.0 op_sel:[0,1,0]
	v_cvt_scalef32_pk_f32_fp4 v[140:141], v238, 1.0 op_sel:[1,1,0]
	v_pk_fma_f32 v[80:81], v[130:131], v[134:135], v[80:81] op_sel_hi:[0,1,1]
	v_pk_fma_f32 v[78:79], v[130:131], v[136:137], v[78:79] op_sel_hi:[0,1,1]
	v_pk_fma_f32 v[76:77], v[130:131], v[138:139], v[76:77] op_sel_hi:[0,1,1]
	v_pk_fma_f32 v[74:75], v[130:131], v[140:141], v[74:75] op_sel_hi:[0,1,1]
	v_cvt_scalef32_pk_f32_fp4 v[134:135], v239, 1.0
	v_cvt_scalef32_pk_f32_fp4 v[136:137], v239, 1.0 op_sel:[1,0,0]
	v_cvt_scalef32_pk_f32_fp4 v[138:139], v239, 1.0 op_sel:[0,1,0]
	v_cvt_scalef32_pk_f32_fp4 v[140:141], v239, 1.0 op_sel:[1,1,0]
	v_pk_fma_f32 v[72:73], v[130:131], v[134:135], v[72:73] op_sel_hi:[0,1,1]
	v_pk_fma_f32 v[70:71], v[130:131], v[136:137], v[70:71] op_sel_hi:[0,1,1]
	v_pk_fma_f32 v[68:69], v[130:131], v[138:139], v[68:69] op_sel_hi:[0,1,1]
	v_pk_fma_f32 v[66:67], v[130:131], v[140:141], v[66:67] op_sel_hi:[0,1,1]
	s_waitcnt vmcnt(2)
	v_cvt_scalef32_pk_f32_fp4 v[134:135], v240, 1.0
	v_cvt_scalef32_pk_f32_fp4 v[136:137], v240, 1.0 op_sel:[1,0,0]
	v_cvt_scalef32_pk_f32_fp4 v[138:139], v240, 1.0 op_sel:[0,1,0]
	v_cvt_scalef32_pk_f32_fp4 v[140:141], v240, 1.0 op_sel:[1,1,0]
	v_pk_fma_f32 v[34:35], v[130:131], v[134:135], v[34:35] op_sel_hi:[0,1,1]
	v_pk_fma_f32 v[36:37], v[130:131], v[136:137], v[36:37] op_sel_hi:[0,1,1]
	v_pk_fma_f32 v[38:39], v[130:131], v[138:139], v[38:39] op_sel_hi:[0,1,1]
	v_pk_fma_f32 v[40:41], v[130:131], v[140:141], v[40:41] op_sel_hi:[0,1,1]
	v_cvt_scalef32_pk_f32_fp4 v[134:135], v241, 1.0
	v_cvt_scalef32_pk_f32_fp4 v[136:137], v241, 1.0 op_sel:[1,0,0]
	v_cvt_scalef32_pk_f32_fp4 v[138:139], v241, 1.0 op_sel:[0,1,0]
	v_cvt_scalef32_pk_f32_fp4 v[140:141], v241, 1.0 op_sel:[1,1,0]
	v_pk_fma_f32 v[42:43], v[130:131], v[134:135], v[42:43] op_sel_hi:[0,1,1]
	v_pk_fma_f32 v[44:45], v[130:131], v[136:137], v[44:45] op_sel_hi:[0,1,1]
	v_pk_fma_f32 v[46:47], v[130:131], v[138:139], v[46:47] op_sel_hi:[0,1,1]
	v_pk_fma_f32 v[48:49], v[130:131], v[140:141], v[48:49] op_sel_hi:[0,1,1]
	v_cvt_scalef32_pk_f32_fp4 v[134:135], v242, 1.0
	v_cvt_scalef32_pk_f32_fp4 v[136:137], v242, 1.0 op_sel:[1,0,0]
	v_cvt_scalef32_pk_f32_fp4 v[138:139], v242, 1.0 op_sel:[0,1,0]
	v_cvt_scalef32_pk_f32_fp4 v[140:141], v242, 1.0 op_sel:[1,1,0]
	v_pk_fma_f32 v[50:51], v[130:131], v[134:135], v[50:51] op_sel_hi:[0,1,1]
	v_pk_fma_f32 v[52:53], v[130:131], v[136:137], v[52:53] op_sel_hi:[0,1,1]
	v_pk_fma_f32 v[54:55], v[130:131], v[138:139], v[54:55] op_sel_hi:[0,1,1]
	v_pk_fma_f32 v[56:57], v[130:131], v[140:141], v[56:57] op_sel_hi:[0,1,1]
	v_cvt_scalef32_pk_f32_fp4 v[134:135], v243, 1.0
	v_cvt_scalef32_pk_f32_fp4 v[136:137], v243, 1.0 op_sel:[1,0,0]
	v_cvt_scalef32_pk_f32_fp4 v[138:139], v243, 1.0 op_sel:[0,1,0]
	v_cvt_scalef32_pk_f32_fp4 v[140:141], v243, 1.0 op_sel:[1,1,0]
	v_pk_fma_f32 v[58:59], v[130:131], v[134:135], v[58:59] op_sel_hi:[0,1,1]
	v_pk_fma_f32 v[60:61], v[130:131], v[136:137], v[60:61] op_sel_hi:[0,1,1]
	v_pk_fma_f32 v[62:63], v[130:131], v[138:139], v[62:63] op_sel_hi:[0,1,1]
	v_pk_fma_f32 v[64:65], v[130:131], v[140:141], v[64:65] op_sel_hi:[0,1,1]
	ds_read_b32 v130, v132 offset:112
	s_waitcnt vmcnt(1)
	v_cvt_scalef32_pk_f32_fp4 v[134:135], v244, 1.0
	v_cvt_scalef32_pk_f32_fp4 v[136:137], v244, 1.0 op_sel:[1,0,0]
	v_cvt_scalef32_pk_f32_fp4 v[138:139], v244, 1.0 op_sel:[0,1,0]
	v_cvt_scalef32_pk_f32_fp4 v[140:141], v244, 1.0 op_sel:[1,1,0]
	s_waitcnt lgkmcnt(0)
	v_pk_fma_f32 v[128:129], v[130:131], v[134:135], v[128:129] op_sel_hi:[0,1,1]
	v_pk_fma_f32 v[126:127], v[130:131], v[136:137], v[126:127] op_sel_hi:[0,1,1]
	v_pk_fma_f32 v[122:123], v[130:131], v[138:139], v[122:123] op_sel_hi:[0,1,1]
	v_pk_fma_f32 v[120:121], v[130:131], v[140:141], v[120:121] op_sel_hi:[0,1,1]
	v_cvt_scalef32_pk_f32_fp4 v[134:135], v245, 1.0
	v_cvt_scalef32_pk_f32_fp4 v[136:137], v245, 1.0 op_sel:[1,0,0]
	v_cvt_scalef32_pk_f32_fp4 v[138:139], v245, 1.0 op_sel:[0,1,0]
	v_cvt_scalef32_pk_f32_fp4 v[140:141], v245, 1.0 op_sel:[1,1,0]
	v_pk_fma_f32 v[118:119], v[130:131], v[134:135], v[118:119] op_sel_hi:[0,1,1]
	v_pk_fma_f32 v[116:117], v[130:131], v[136:137], v[116:117] op_sel_hi:[0,1,1]
	v_pk_fma_f32 v[114:115], v[130:131], v[138:139], v[114:115] op_sel_hi:[0,1,1]
	v_pk_fma_f32 v[112:113], v[130:131], v[140:141], v[112:113] op_sel_hi:[0,1,1]
	v_cvt_scalef32_pk_f32_fp4 v[134:135], v246, 1.0
	v_cvt_scalef32_pk_f32_fp4 v[136:137], v246, 1.0 op_sel:[1,0,0]
	v_cvt_scalef32_pk_f32_fp4 v[138:139], v246, 1.0 op_sel:[0,1,0]
	v_cvt_scalef32_pk_f32_fp4 v[140:141], v246, 1.0 op_sel:[1,1,0]
	v_pk_fma_f32 v[80:81], v[130:131], v[134:135], v[80:81] op_sel_hi:[0,1,1]
	v_pk_fma_f32 v[78:79], v[130:131], v[136:137], v[78:79] op_sel_hi:[0,1,1]
	v_pk_fma_f32 v[76:77], v[130:131], v[138:139], v[76:77] op_sel_hi:[0,1,1]
	v_pk_fma_f32 v[74:75], v[130:131], v[140:141], v[74:75] op_sel_hi:[0,1,1]
	v_cvt_scalef32_pk_f32_fp4 v[134:135], v247, 1.0
	v_cvt_scalef32_pk_f32_fp4 v[136:137], v247, 1.0 op_sel:[1,0,0]
	v_cvt_scalef32_pk_f32_fp4 v[138:139], v247, 1.0 op_sel:[0,1,0]
	v_cvt_scalef32_pk_f32_fp4 v[140:141], v247, 1.0 op_sel:[1,1,0]
	v_pk_fma_f32 v[72:73], v[130:131], v[134:135], v[72:73] op_sel_hi:[0,1,1]
	v_pk_fma_f32 v[70:71], v[130:131], v[136:137], v[70:71] op_sel_hi:[0,1,1]
	v_pk_fma_f32 v[68:69], v[130:131], v[138:139], v[68:69] op_sel_hi:[0,1,1]
	v_pk_fma_f32 v[66:67], v[130:131], v[140:141], v[66:67] op_sel_hi:[0,1,1]
	s_waitcnt vmcnt(0)
	v_cvt_scalef32_pk_f32_fp4 v[134:135], v228, 1.0
	v_cvt_scalef32_pk_f32_fp4 v[136:137], v228, 1.0 op_sel:[1,0,0]
	v_cvt_scalef32_pk_f32_fp4 v[138:139], v228, 1.0 op_sel:[0,1,0]
	v_cvt_scalef32_pk_f32_fp4 v[140:141], v228, 1.0 op_sel:[1,1,0]
	v_pk_fma_f32 v[34:35], v[130:131], v[134:135], v[34:35] op_sel_hi:[0,1,1]
	v_pk_fma_f32 v[36:37], v[130:131], v[136:137], v[36:37] op_sel_hi:[0,1,1]
	v_pk_fma_f32 v[38:39], v[130:131], v[138:139], v[38:39] op_sel_hi:[0,1,1]
	v_pk_fma_f32 v[40:41], v[130:131], v[140:141], v[40:41] op_sel_hi:[0,1,1]
	v_cvt_scalef32_pk_f32_fp4 v[134:135], v229, 1.0
	v_cvt_scalef32_pk_f32_fp4 v[136:137], v229, 1.0 op_sel:[1,0,0]
	v_cvt_scalef32_pk_f32_fp4 v[138:139], v229, 1.0 op_sel:[0,1,0]
	v_cvt_scalef32_pk_f32_fp4 v[140:141], v229, 1.0 op_sel:[1,1,0]
	v_pk_fma_f32 v[42:43], v[130:131], v[134:135], v[42:43] op_sel_hi:[0,1,1]
	v_pk_fma_f32 v[44:45], v[130:131], v[136:137], v[44:45] op_sel_hi:[0,1,1]
	v_pk_fma_f32 v[46:47], v[130:131], v[138:139], v[46:47] op_sel_hi:[0,1,1]
	v_pk_fma_f32 v[48:49], v[130:131], v[140:141], v[48:49] op_sel_hi:[0,1,1]
	v_cvt_scalef32_pk_f32_fp4 v[134:135], v230, 1.0
	v_cvt_scalef32_pk_f32_fp4 v[136:137], v230, 1.0 op_sel:[1,0,0]
	v_cvt_scalef32_pk_f32_fp4 v[138:139], v230, 1.0 op_sel:[0,1,0]
	v_cvt_scalef32_pk_f32_fp4 v[140:141], v230, 1.0 op_sel:[1,1,0]
	v_pk_fma_f32 v[50:51], v[130:131], v[134:135], v[50:51] op_sel_hi:[0,1,1]
	v_pk_fma_f32 v[52:53], v[130:131], v[136:137], v[52:53] op_sel_hi:[0,1,1]
	v_pk_fma_f32 v[54:55], v[130:131], v[138:139], v[54:55] op_sel_hi:[0,1,1]
	v_pk_fma_f32 v[56:57], v[130:131], v[140:141], v[56:57] op_sel_hi:[0,1,1]
	v_cvt_scalef32_pk_f32_fp4 v[134:135], v231, 1.0
	v_cvt_scalef32_pk_f32_fp4 v[136:137], v231, 1.0 op_sel:[1,0,0]
	v_cvt_scalef32_pk_f32_fp4 v[138:139], v231, 1.0 op_sel:[0,1,0]
	v_cvt_scalef32_pk_f32_fp4 v[140:141], v231, 1.0 op_sel:[1,1,0]
	v_pk_fma_f32 v[58:59], v[130:131], v[134:135], v[58:59] op_sel_hi:[0,1,1]
	v_pk_fma_f32 v[60:61], v[130:131], v[136:137], v[60:61] op_sel_hi:[0,1,1]
	v_pk_fma_f32 v[62:63], v[130:131], v[138:139], v[62:63] op_sel_hi:[0,1,1]
	v_pk_fma_f32 v[64:65], v[130:131], v[140:141], v[64:65] op_sel_hi:[0,1,1]
	s_setprio 0
	v_lshrrev_b32_e32 v2, 1, v125
	v_and_b32_e32 v3, 1, v125
	v_lshlrev_b32_e32 v2, 9, v2
	v_lshl_add_u32 v2, v3, 4, v2
	v_lshlrev_b64 v[94:95], 10, v[94:95]
	v_or_b32_e32 v94, v94, v82
	v_add_u32_e32 v94, v94, v2
	v_lshlrev_b64 v[130:131], 2, v[94:95]
	v_lshl_add_u64 v[132:133], s[18:19], 0, v[130:131]
	global_load_dwordx4 v[4:7], v[132:133], off
	global_load_dwordx4 v[8:11], v[132:133], off offset:16
	global_load_dwordx4 v[12:15], v[132:133], off offset:32
	global_load_dwordx4 v[16:19], v[132:133], off offset:48
	v_lshlrev_b32_e32 v2, 2, v2
	v_mov_b32_e32 v3, 0
	v_lshl_add_u64 v[20:21], v[88:89], 0, v[2:3]
	global_load_dwordx4 v[134:137], v[20:21], off
	global_load_dwordx4 v[138:141], v[20:21], off offset:16
	global_load_dwordx4 v[142:145], v[20:21], off offset:32
	global_load_dwordx4 v[146:149], v[20:21], off offset:48
	v_readlane_b32 s60, v254, 29
	v_readlane_b32 s61, v254, 30
	v_readlane_b32 s62, v254, 31
	v_readlane_b32 s63, v254, 32
	v_lshl_add_u64 v[22:23], s[20:21], 0, v[130:131]
	v_lshl_add_u64 v[26:27], v[94:95], 1, s[16:17]
	v_permlane16_swap_b32_e32 v128, v80
	v_permlane16_swap_b32_e32 v129, v81
	v_pk_add_f32 v[128:129], v[128:129], v[80:81]
	v_permlane16_swap_b32_e32 v126, v78
	v_permlane16_swap_b32_e32 v127, v79
	v_pk_add_f32 v[126:127], v[126:127], v[78:79]
	v_permlane16_swap_b32_e32 v122, v76
	v_permlane16_swap_b32_e32 v123, v77
	v_pk_add_f32 v[122:123], v[122:123], v[76:77]
	v_permlane16_swap_b32_e32 v120, v74
	v_permlane16_swap_b32_e32 v121, v75
	v_pk_add_f32 v[120:121], v[120:121], v[74:75]
	v_permlane16_swap_b32_e32 v118, v72
	v_permlane16_swap_b32_e32 v119, v73
	v_pk_add_f32 v[118:119], v[118:119], v[72:73]
	v_permlane16_swap_b32_e32 v116, v70
	v_permlane16_swap_b32_e32 v117, v71
	v_pk_add_f32 v[116:117], v[116:117], v[70:71]
	v_permlane16_swap_b32_e32 v114, v68
	v_permlane16_swap_b32_e32 v115, v69
	v_pk_add_f32 v[114:115], v[114:115], v[68:69]
	v_permlane16_swap_b32_e32 v112, v66
	v_permlane16_swap_b32_e32 v113, v67
	v_pk_add_f32 v[112:113], v[112:113], v[66:67]
	v_permlane16_swap_b32_e32 v34, v50
	v_permlane16_swap_b32_e32 v35, v51
	v_pk_add_f32 v[34:35], v[34:35], v[50:51]
	v_permlane16_swap_b32_e32 v36, v52
	v_permlane16_swap_b32_e32 v37, v53
	v_pk_add_f32 v[36:37], v[36:37], v[52:53]
	v_permlane16_swap_b32_e32 v38, v54
	v_permlane16_swap_b32_e32 v39, v55
	v_pk_add_f32 v[38:39], v[38:39], v[54:55]
	v_permlane16_swap_b32_e32 v40, v56
	v_permlane16_swap_b32_e32 v41, v57
	v_pk_add_f32 v[40:41], v[40:41], v[56:57]
	v_permlane16_swap_b32_e32 v42, v58
	v_permlane16_swap_b32_e32 v43, v59
	v_pk_add_f32 v[42:43], v[42:43], v[58:59]
	v_permlane16_swap_b32_e32 v44, v60
	v_permlane16_swap_b32_e32 v45, v61
	v_pk_add_f32 v[44:45], v[44:45], v[60:61]
	v_permlane16_swap_b32_e32 v46, v62
	v_permlane16_swap_b32_e32 v47, v63
	v_pk_add_f32 v[46:47], v[46:47], v[62:63]
	v_permlane16_swap_b32_e32 v48, v64
	v_permlane16_swap_b32_e32 v49, v65
	v_pk_add_f32 v[48:49], v[48:49], v[64:65]
	v_permlane32_swap_b32_e32 v128, v34
	v_permlane32_swap_b32_e32 v129, v35
	v_pk_add_f32 v[128:129], v[128:129], v[34:35]
	v_permlane32_swap_b32_e32 v126, v36
	v_permlane32_swap_b32_e32 v127, v37
	v_pk_add_f32 v[126:127], v[126:127], v[36:37]
	v_permlane32_swap_b32_e32 v122, v38
	v_permlane32_swap_b32_e32 v123, v39
	v_pk_add_f32 v[122:123], v[122:123], v[38:39]
	v_permlane32_swap_b32_e32 v120, v40
	v_permlane32_swap_b32_e32 v121, v41
	v_pk_add_f32 v[120:121], v[120:121], v[40:41]
	v_permlane32_swap_b32_e32 v118, v42
	v_permlane32_swap_b32_e32 v119, v43
	v_pk_add_f32 v[118:119], v[118:119], v[42:43]
	v_permlane32_swap_b32_e32 v116, v44
	v_permlane32_swap_b32_e32 v117, v45
	v_pk_add_f32 v[116:117], v[116:117], v[44:45]
	v_permlane32_swap_b32_e32 v114, v46
	v_permlane32_swap_b32_e32 v115, v47
	v_pk_add_f32 v[114:115], v[114:115], v[46:47]
	v_permlane32_swap_b32_e32 v112, v48
	v_permlane32_swap_b32_e32 v113, v49
	v_pk_add_f32 v[112:113], v[112:113], v[48:49]
	v_lshl_add_u64 v[24:25], s[60:61], 0, v[130:131]
	s_waitcnt vmcnt(4)
	v_pk_add_f32 v[228:229], v[4:5], v[128:129]
	v_pk_add_f32 v[230:231], v[6:7], v[126:127]
	v_pk_add_f32 v[232:233], v[8:9], v[122:123]
	v_pk_add_f32 v[234:235], v[10:11], v[120:121]
	v_pk_add_f32 v[236:237], v[12:13], v[118:119]
	v_pk_add_f32 v[238:239], v[14:15], v[116:117]
	v_pk_add_f32 v[240:241], v[16:17], v[114:115]
	v_pk_add_f32 v[242:243], v[18:19], v[112:113]
	v_pk_mul_f32 v[244:245], v[228:229], v[228:229]
	v_pk_fma_f32 v[244:245], v[230:231], v[230:231], v[244:245]
	v_pk_fma_f32 v[244:245], v[232:233], v[232:233], v[244:245]
	v_pk_fma_f32 v[244:245], v[234:235], v[234:235], v[244:245]
	v_pk_fma_f32 v[244:245], v[236:237], v[236:237], v[244:245]
	v_pk_fma_f32 v[244:245], v[238:239], v[238:239], v[244:245]
	v_pk_fma_f32 v[244:245], v[240:241], v[240:241], v[244:245]
	v_pk_fma_f32 v[244:245], v[242:243], v[242:243], v[244:245]
	v_add_f32_e32 v244, v244, v245
	ds_bpermute_b32 v245, v207, v244
	s_waitcnt lgkmcnt(0)
	v_add_f32_e32 v244, v244, v245
	ds_bpermute_b32 v245, v208, v244
	s_waitcnt lgkmcnt(0)
	v_add_f32_e32 v244, v244, v245
	ds_bpermute_b32 v245, v209, v244
	s_waitcnt lgkmcnt(0)
	v_add_f32_e32 v244, v244, v245
	ds_bpermute_b32 v245, v210, v244
	s_waitcnt lgkmcnt(0)
	v_add_f32_e32 v244, v244, v245
	ds_bpermute_b32 v245, v211, v244
	s_waitcnt lgkmcnt(0)
	v_add_f32_e32 v244, v244, v245
	ds_bpermute_b32 v245, v212, v244
	s_waitcnt lgkmcnt(0)
	v_add_f32_e32 v244, v244, v245
	v_fmamk_f32 v244, v244, 0x3a800000, v172
	v_mul_f32_e32 v245, 0x4b800000, v244
	v_cmp_gt_f32_e32 vcc, s96, v244
	s_nop 1
	v_cndmask_b32_e32 v244, v244, v245, vcc
	v_rsq_f32_e32 v244, v244
	s_nop 0
	v_mul_f32_e32 v245, 0x45800000, v244
	v_cndmask_b32_e32 v246, v244, v245, vcc
	s_waitcnt vmcnt(0)
	v_pk_mul_f32 v[134:135], v[246:247], v[134:135] op_sel_hi:[0,1]
	v_pk_mul_f32 v[136:137], v[246:247], v[136:137] op_sel_hi:[0,1]
	v_pk_mul_f32 v[138:139], v[246:247], v[138:139] op_sel_hi:[0,1]
	v_pk_mul_f32 v[140:141], v[246:247], v[140:141] op_sel_hi:[0,1]
	v_pk_mul_f32 v[142:143], v[246:247], v[142:143] op_sel_hi:[0,1]
	v_pk_mul_f32 v[144:145], v[246:247], v[144:145] op_sel_hi:[0,1]
	v_pk_mul_f32 v[146:147], v[246:247], v[146:147] op_sel_hi:[0,1]
	v_pk_mul_f32 v[148:149], v[246:247], v[148:149] op_sel_hi:[0,1]
	v_pk_mul_f32 v[134:135], v[228:229], v[134:135]
	v_pk_mul_f32 v[136:137], v[230:231], v[136:137]
	v_pk_mul_f32 v[138:139], v[232:233], v[138:139]
	v_pk_mul_f32 v[140:141], v[234:235], v[140:141]
	v_pk_mul_f32 v[142:143], v[236:237], v[142:143]
	v_pk_mul_f32 v[144:145], v[238:239], v[144:145]
	v_pk_mul_f32 v[146:147], v[240:241], v[146:147]
	v_pk_mul_f32 v[148:149], v[242:243], v[148:149]
	s_andn2_b64 vcc, exec, s[22:23]
	s_cbranch_vccnz .Lpe_mid
	global_store_dwordx4 v[24:25], v[134:137], off
	global_store_dwordx4 v[24:25], v[138:141], off offset:16
	global_store_dwordx4 v[24:25], v[142:145], off offset:32
	global_store_dwordx4 v[24:25], v[146:149], off offset:48
	s_branch .Lpe_done
